# conv mixer + SSD combine row kernels: no clamped dummy prefetches at the tail (tail mode drains with vmcnt(0))
# speedup vs baseline: 1.0043x; 1.0043x over previous
; __device__ __forceinline__ int ltid() { int t = threadIdx.x; asm volatile("" : "+v"(t)); return t; }
; __device__ __forceinline__ int lbid() { int t = blockIdx.x; asm volatile("" : "+s"(t)); return t; }
; __device__ __forceinline__ void ssd_combine_rows(CArgs a, int G) {
;     const int lane = ltid() & 63, wave = ltid() >> 6;
;     const int gw = lbid() * NWAVES + wave, NGW = G * NWAVES;
;     const unsigned char* WSB = a->ws;
;     const bf16_t* U = (const bf16_t*)(a->ws + WS_U); bf16_t* Y = (bf16_t*)(a->ws + WS_Y);
;     const bf16_t* yb = (const bf16_t*)(a->ws + WS_YF);
;     const int c0 = lane * 16;
;     auto load = [&](int row, u32x4 (&raw)[6]) {
; #pragma unroll
;         for (int hf = 0; hf < 2; ++hf) { raw[3 * hf] = *(const u32x4*)(Y + (size_t)row * 2048 + c0 + 8 * hf); raw[3 * hf + 1] = *(const u32x4*)(yb + (size_t)row * 1024 + c0 + 8 * hf);
;             raw[3 * hf + 2] = *(const u32x4*)(U + (size_t)row * NU + UZ + c0 + 8 * hf); }
;     };
;     ...
;     for (int row = gw; row < T; row += 2 * NGW) {
;         const int row2 = row + NGW;
;         u32x4 ra[6], rb[6];
;         load(row, ra);
;         if (row2 < T) load(row2, rb);
.LBB0_83:
	v_readlane_b32 s2, v255, 42
	s_nop 3
	s_cmp_eq_u32 s2, 2
	s_cbranch_scc1 .Lp5_done
	s_load_dwordx2 s[60:61], s[6:7], 0xe8
	v_readfirstlane_b32 s10, v244
	v_and_b32_e32 v2, 63, v244
	v_lshlrev_b32_e32 v2, 4, v2
	v_readlane_b32 s11, v253, 0
	s_lshr_b32 s10, s10, 6
	s_nop 3
	s_lshl_b32 s11, s11, 3
	s_add_i32 s10, s10, s11
	s_lshl_b32 s11, s64, 3
	s_waitcnt lgkmcnt(0)
	s_and_b32 s61, s61, 0xffff
	s_cmp_lt_u32 s10, 0x4000
	s_cbranch_scc0 .Lcmb_done
	s_mov_b32 s22, 0
	s_lshl_b32 s16, s10, 12
	s_add_u32 s16, s16, 0x10a00000
	s_lshl_b32 s17, s10, 11
	s_add_u32 s17, s17, 0x18a00000
	s_mul_i32 s18, s10, 0x2400
	s_add_u32 s18, s18, 0x3a00000
	buffer_load_dwordx4 v[8:11], v2, s[60:63], s16 offen
	buffer_load_dwordx4 v[12:15], v2, s[60:63], s16 offen offset:1024
	buffer_load_dwordx4 v[16:19], v2, s[60:63], s17 offen
	buffer_load_dwordx4 v[20:23], v2, s[60:63], s17 offen offset:1024
	buffer_load_dwordx4 v[24:27], v2, s[60:63], s18 offen
	buffer_load_dwordx4 v[28:31], v2, s[60:63], s18 offen offset:1024
	s_mul_i32 s12, s11, 1
	s_add_i32 s12, s10, s12
	s_cmp_lt_u32 s12, 0x4000
	s_cbranch_scc0 .Lcmb_pfskip_1
	s_lshl_b32 s16, s12, 12
	s_add_u32 s16, s16, 0x10a00000
	s_lshl_b32 s17, s12, 11
	s_add_u32 s17, s17, 0x18a00000
	s_mul_i32 s18, s12, 0x2400
	s_add_u32 s18, s18, 0x3a00000
	buffer_load_dwordx4 v[32:35], v2, s[60:63], s16 offen
	buffer_load_dwordx4 v[36:39], v2, s[60:63], s16 offen offset:1024
	buffer_load_dwordx4 v[40:43], v2, s[60:63], s17 offen
	buffer_load_dwordx4 v[44:47], v2, s[60:63], s17 offen offset:1024
	buffer_load_dwordx4 v[48:51], v2, s[60:63], s18 offen
	buffer_load_dwordx4 v[52:55], v2, s[60:63], s18 offen offset:1024
	s_branch .Lcmb_pfdone_1
.Lcmb_pfskip_1:
	s_mov_b32 s22, 1
.Lcmb_pfdone_1:
	s_mul_i32 s12, s11, 2
	s_add_i32 s12, s10, s12
	s_cmp_lt_u32 s12, 0x4000
	s_cbranch_scc0 .Lcmb_pfskip_2
	s_lshl_b32 s16, s12, 12
	s_add_u32 s16, s16, 0x10a00000
	s_lshl_b32 s17, s12, 11
	s_add_u32 s17, s17, 0x18a00000
	s_mul_i32 s18, s12, 0x2400
	s_add_u32 s18, s18, 0x3a00000
	buffer_load_dwordx4 v[56:59], v2, s[60:63], s16 offen
	buffer_load_dwordx4 v[60:63], v2, s[60:63], s16 offen offset:1024
	buffer_load_dwordx4 v[64:67], v2, s[60:63], s17 offen
	buffer_load_dwordx4 v[68:71], v2, s[60:63], s17 offen offset:1024
	buffer_load_dwordx4 v[72:75], v2, s[60:63], s18 offen
	buffer_load_dwordx4 v[76:79], v2, s[60:63], s18 offen offset:1024
	s_branch .Lcmb_pfdone_2

; __device__ __forceinline__ float silu_f(float x) { return x * __builtin_amdgcn_rcpf(1.f + __expf(-x)); }
; __device__ __forceinline__ void ssd_combine_rows(CArgs a, int G) {
;     ...
;     auto finish = [&](int row, const u32x4 (&raw)[6]) {
;         float g[16]; float ss = 0.f;
; #pragma unroll
;         for (int hf = 0; hf < 2; ++hf) {
;             float f[8], bb[8], z[8];
;             unpack8(raw[3 * hf], f); unpack8(raw[3 * hf + 1], bb); unpack8(raw[3 * hf + 2], z);
; #pragma unroll
;             for (int e = 0; e < 8; ++e) { const float y = (f[e] + bb[e]) * silu_f(z[e]); g[8 * hf + e] = y; ss += y * y; }
;         }
.Lcmb_pfdone_2:
	s_cmp_eq_u32 s22, 0
	s_cbranch_scc1 .Lcmb_wc_3
	s_waitcnt vmcnt(0)
	s_branch .Lcmb_wg_3
.Lcmb_wc_3:
	s_waitcnt vmcnt(12)
.Lcmb_wg_3:
	v_lshlrev_b32_e32 v96, 16, v24
	v_and_b32_e32 v97, 0xffff0000, v24
	v_lshlrev_b32_e32 v98, 16, v25
	v_and_b32_e32 v99, 0xffff0000, v25
	v_lshlrev_b32_e32 v100, 16, v26
	v_and_b32_e32 v101, 0xffff0000, v26
	v_lshlrev_b32_e32 v102, 16, v27
	v_and_b32_e32 v103, 0xffff0000, v27
	v_mul_f32_e32 v104, 0xbfb8aa3b, v96
	v_mul_f32_e32 v105, 0xbfb8aa3b, v97
	v_mul_f32_e32 v106, 0xbfb8aa3b, v98
	v_mul_f32_e32 v107, 0xbfb8aa3b, v99
	v_mul_f32_e32 v108, 0xbfb8aa3b, v100
	v_mul_f32_e32 v109, 0xbfb8aa3b, v101
	v_mul_f32_e32 v110, 0xbfb8aa3b, v102
	v_mul_f32_e32 v111, 0xbfb8aa3b, v103
	v_exp_f32_e32 v104, v104
	v_exp_f32_e32 v105, v105
	v_exp_f32_e32 v106, v106
	v_exp_f32_e32 v107, v107
	v_exp_f32_e32 v108, v108
	v_exp_f32_e32 v109, v109
	v_exp_f32_e32 v110, v110
	v_exp_f32_e32 v111, v111
	v_lshlrev_b32_e32 v112, 16, v8
	v_and_b32_e32 v113, 0xffff0000, v8
	v_lshlrev_b32_e32 v114, 16, v9
	v_and_b32_e32 v115, 0xffff0000, v9
	v_lshlrev_b32_e32 v116, 16, v10
	v_and_b32_e32 v117, 0xffff0000, v10
	v_lshlrev_b32_e32 v118, 16, v11
	v_and_b32_e32 v119, 0xffff0000, v11
	v_lshlrev_b32_e32 v120, 16, v16
	v_and_b32_e32 v121, 0xffff0000, v16
	v_lshlrev_b32_e32 v122, 16, v17
	v_and_b32_e32 v123, 0xffff0000, v17
	v_lshlrev_b32_e32 v124, 16, v18
	v_and_b32_e32 v125, 0xffff0000, v18
	v_lshlrev_b32_e32 v126, 16, v19
	v_and_b32_e32 v127, 0xffff0000, v19
	v_add_f32_e32 v112, v112, v120
	v_add_f32_e32 v113, v113, v121
	v_add_f32_e32 v114, v114, v122
	v_add_f32_e32 v115, v115, v123
	v_add_f32_e32 v116, v116, v124
	v_add_f32_e32 v117, v117, v125
	v_add_f32_e32 v118, v118, v126
	v_add_f32_e32 v119, v119, v127
	v_add_f32_e32 v104, 1.0, v104
	v_add_f32_e32 v105, 1.0, v105
	v_add_f32_e32 v106, 1.0, v106
	v_add_f32_e32 v107, 1.0, v107
	v_add_f32_e32 v108, 1.0, v108
	v_add_f32_e32 v109, 1.0, v109
	v_add_f32_e32 v110, 1.0, v110
	v_add_f32_e32 v111, 1.0, v111
	v_rcp_f32_e32 v104, v104
	v_rcp_f32_e32 v105, v105
	v_rcp_f32_e32 v106, v106
	v_rcp_f32_e32 v107, v107
	v_rcp_f32_e32 v108, v108
	v_rcp_f32_e32 v109, v109
	v_rcp_f32_e32 v110, v110
	v_rcp_f32_e32 v111, v111
	v_mul_f32_e32 v96, v96, v104
	v_mul_f32_e32 v97, v97, v105
	v_mul_f32_e32 v98, v98, v106
	v_mul_f32_e32 v99, v99, v107
	v_mul_f32_e32 v100, v100, v108
	v_mul_f32_e32 v101, v101, v109
	v_mul_f32_e32 v102, v102, v110
	v_mul_f32_e32 v103, v103, v111
	v_mul_f32_e32 v80, v112, v96
	v_mul_f32_e32 v81, v113, v97
	v_mul_f32_e32 v82, v114, v98
	v_mul_f32_e32 v83, v115, v99
	v_mul_f32_e32 v84, v116, v100
	v_mul_f32_e32 v85, v117, v101
	v_mul_f32_e32 v86, v118, v102
	v_mul_f32_e32 v87, v119, v103
	v_mul_f32_e32 v128, v80, v80
	v_fmac_f32_e32 v128, v81, v81
	v_fmac_f32_e32 v128, v82, v82
	v_fmac_f32_e32 v128, v83, v83
	v_fmac_f32_e32 v128, v84, v84
	v_fmac_f32_e32 v128, v85, v85
	v_fmac_f32_e32 v128, v86, v86
	v_fmac_f32_e32 v128, v87, v87
	v_lshlrev_b32_e32 v96, 16, v28
	v_and_b32_e32 v97, 0xffff0000, v28
	v_lshlrev_b32_e32 v98, 16, v29
	v_and_b32_e32 v99, 0xffff0000, v29
	v_lshlrev_b32_e32 v100, 16, v30
	v_and_b32_e32 v101, 0xffff0000, v30
	v_lshlrev_b32_e32 v102, 16, v31
	v_and_b32_e32 v103, 0xffff0000, v31
	v_mul_f32_e32 v104, 0xbfb8aa3b, v96
	v_mul_f32_e32 v105, 0xbfb8aa3b, v97
	v_mul_f32_e32 v106, 0xbfb8aa3b, v98
	v_mul_f32_e32 v107, 0xbfb8aa3b, v99
	v_mul_f32_e32 v108, 0xbfb8aa3b, v100
	v_mul_f32_e32 v109, 0xbfb8aa3b, v101
	v_mul_f32_e32 v110, 0xbfb8aa3b, v102
	v_mul_f32_e32 v111, 0xbfb8aa3b, v103
	v_exp_f32_e32 v104, v104
	v_exp_f32_e32 v105, v105
	v_exp_f32_e32 v106, v106
	v_exp_f32_e32 v107, v107
	v_exp_f32_e32 v108, v108
	v_exp_f32_e32 v109, v109
	v_exp_f32_e32 v110, v110
	v_exp_f32_e32 v111, v111
	v_lshlrev_b32_e32 v112, 16, v12
	v_and_b32_e32 v113, 0xffff0000, v12
	v_lshlrev_b32_e32 v114, 16, v13
	v_and_b32_e32 v115, 0xffff0000, v13
	v_lshlrev_b32_e32 v116, 16, v14
	v_and_b32_e32 v117, 0xffff0000, v14
	v_lshlrev_b32_e32 v118, 16, v15
	v_and_b32_e32 v119, 0xffff0000, v15
	v_lshlrev_b32_e32 v120, 16, v20
	v_and_b32_e32 v121, 0xffff0000, v20
	v_lshlrev_b32_e32 v122, 16, v21
	v_and_b32_e32 v123, 0xffff0000, v21
	v_lshlrev_b32_e32 v124, 16, v22
	v_and_b32_e32 v125, 0xffff0000, v22
	v_lshlrev_b32_e32 v126, 16, v23
	v_and_b32_e32 v127, 0xffff0000, v23
	v_add_f32_e32 v112, v112, v120
; #define wt16(p, v) wt16b(WSB, (p), (v))
; __device__ __forceinline__ u32x4 pack8(const float (&f)[8]) { u32x4 v; v.x = cvt_pk_bf16(f[0], f[1]); v.y = cvt_pk_bf16(f[2], f[3]); v.z = cvt_pk_bf16(f[4], f[5]); v.w = cvt_pk_bf16(f[6], f[7]); return v; }
; __device__ __forceinline__ void ssd_combine_rows(CArgs a, int G) {
;     ...
;         ss += __shfl_xor(ss, 1); ss += __shfl_xor(ss, 2); ss += __shfl_xor(ss, 4); ss += __shfl_xor(ss, 8); ss += __shfl_xor(ss, 16);
;         const float r = rsqrtf(ss * (1.f / 512.f) + EPS);
;         float o0[8], o1[8];
; #pragma unroll
;         for (int e = 0; e < 8; ++e) { o0[e] = g[e] * r; o1[e] = g[8 + e] * r; }
;         wt16(Y + (size_t)row * 2048 + c0, pack8(o0)); wt16(Y + (size_t)row * 2048 + c0 + 8, pack8(o1));
;     };
;     for (int row = gw; row < T; row += 2 * NGW) {
;         const int row2 = row + NGW;
;         u32x4 ra[6], rb[6];
;         load(row, ra);
;         if (row2 < T) load(row2, rb);
;         finish(row, ra);
;         if (row2 < T) finish(row2, rb);
	v_add_f32_e32 v113, v113, v121
	v_add_f32_e32 v114, v114, v122
	v_add_f32_e32 v115, v115, v123
	v_add_f32_e32 v116, v116, v124
	v_add_f32_e32 v117, v117, v125
	v_add_f32_e32 v118, v118, v126
	v_add_f32_e32 v119, v119, v127
	v_add_f32_e32 v104, 1.0, v104
	v_add_f32_e32 v105, 1.0, v105
	v_add_f32_e32 v106, 1.0, v106
	v_add_f32_e32 v107, 1.0, v107
	v_add_f32_e32 v108, 1.0, v108
	v_add_f32_e32 v109, 1.0, v109
	v_add_f32_e32 v110, 1.0, v110
	v_add_f32_e32 v111, 1.0, v111
	v_rcp_f32_e32 v104, v104
	v_rcp_f32_e32 v105, v105
	v_rcp_f32_e32 v106, v106
	v_rcp_f32_e32 v107, v107
	v_rcp_f32_e32 v108, v108
	v_rcp_f32_e32 v109, v109
	v_rcp_f32_e32 v110, v110
	v_rcp_f32_e32 v111, v111
	v_mul_f32_e32 v96, v96, v104
	v_mul_f32_e32 v97, v97, v105
	v_mul_f32_e32 v98, v98, v106
	v_mul_f32_e32 v99, v99, v107
	v_mul_f32_e32 v100, v100, v108
	v_mul_f32_e32 v101, v101, v109
	v_mul_f32_e32 v102, v102, v110
	v_mul_f32_e32 v103, v103, v111
	v_mul_f32_e32 v88, v112, v96
	v_mul_f32_e32 v89, v113, v97
	v_mul_f32_e32 v90, v114, v98
	v_mul_f32_e32 v91, v115, v99
	v_mul_f32_e32 v92, v116, v100
	v_mul_f32_e32 v93, v117, v101
	v_mul_f32_e32 v94, v118, v102
	v_mul_f32_e32 v95, v119, v103
	v_mul_f32_e32 v129, v88, v88
	v_fmac_f32_e32 v129, v89, v89
	v_fmac_f32_e32 v129, v90, v90
	v_fmac_f32_e32 v129, v91, v91
	v_fmac_f32_e32 v129, v92, v92
	v_fmac_f32_e32 v129, v93, v93
	v_fmac_f32_e32 v129, v94, v94
	v_fmac_f32_e32 v129, v95, v95
	s_nop 1
	v_add_f32_dpp v128, v128, v128 row_shr:1 row_mask:0xf bank_mask:0xf bound_ctrl:0
	v_add_f32_dpp v129, v129, v129 row_shr:1 row_mask:0xf bank_mask:0xf bound_ctrl:0
	s_nop 0
	v_add_f32_dpp v128, v128, v128 row_shr:2 row_mask:0xf bank_mask:0xf bound_ctrl:0
	v_add_f32_dpp v129, v129, v129 row_shr:2 row_mask:0xf bank_mask:0xf bound_ctrl:0
	s_nop 0
	v_add_f32_dpp v128, v128, v128 row_shr:4 row_mask:0xf bank_mask:0xf bound_ctrl:0
	v_add_f32_dpp v129, v129, v129 row_shr:4 row_mask:0xf bank_mask:0xf bound_ctrl:0
	s_nop 0
	v_add_f32_dpp v128, v128, v128 row_shr:8 row_mask:0xf bank_mask:0xf bound_ctrl:0
	v_add_f32_dpp v129, v129, v129 row_shr:8 row_mask:0xf bank_mask:0xf bound_ctrl:0
	s_nop 0
	v_add_f32_dpp v128, v128, v128 row_bcast:15 row_mask:0xa bank_mask:0xf
	v_add_f32_dpp v129, v129, v129 row_bcast:15 row_mask:0xa bank_mask:0xf
	s_nop 0
	v_add_f32_dpp v128, v128, v128 row_bcast:31 row_mask:0xc bank_mask:0xf
	v_add_f32_dpp v129, v129, v129 row_bcast:31 row_mask:0xc bank_mask:0xf
	s_nop 0
	s_nop 0
	v_readlane_b32 s20, v128, 63
	v_readlane_b32 s21, v129, 63
	s_nop 1
	v_mov_b32_e32 v130, s20
	v_mov_b32_e32 v131, s21
	v_fmamk_f32 v130, v130, 0x3b000000, v245
	v_fmamk_f32 v131, v131, 0x3b000000, v245
	v_rsq_f32_e32 v130, v130
	v_rsq_f32_e32 v131, v131
	s_nop 0
	v_mul_f32_e32 v80, v80, v130
	v_mul_f32_e32 v81, v81, v130
	v_mul_f32_e32 v82, v82, v130
	v_mul_f32_e32 v83, v83, v130
	v_mul_f32_e32 v84, v84, v130
	v_mul_f32_e32 v85, v85, v130
	v_mul_f32_e32 v86, v86, v130
	v_mul_f32_e32 v87, v87, v130
	v_cvt_pk_bf16_f32 v80, v80, v81
	v_cvt_pk_bf16_f32 v81, v82, v83
	v_cvt_pk_bf16_f32 v82, v84, v85
	v_cvt_pk_bf16_f32 v83, v86, v87
	v_mul_f32_e32 v88, v88, v131
	v_mul_f32_e32 v89, v89, v131
	v_mul_f32_e32 v90, v90, v131
	v_mul_f32_e32 v91, v91, v131
	v_mul_f32_e32 v92, v92, v131
	v_mul_f32_e32 v93, v93, v131
	v_mul_f32_e32 v94, v94, v131
	v_mul_f32_e32 v95, v95, v131
	v_cvt_pk_bf16_f32 v88, v88, v89
	v_cvt_pk_bf16_f32 v89, v90, v91
	v_cvt_pk_bf16_f32 v90, v92, v93
	v_cvt_pk_bf16_f32 v91, v94, v95
	s_lshl_b32 s19, s10, 12
	s_add_u32 s19, s19, 0x10a00000
	buffer_store_dwordx4 v[80:83], v2, s[60:63], s19 offen sc1
	buffer_store_dwordx4 v[88:91], v2, s[60:63], s19 offen offset:1024 sc1
	s_mul_i32 s12, s11, 3
	s_add_i32 s12, s10, s12
	s_cmp_lt_u32 s12, 0x4000
	s_cbranch_scc0 .Lcmb_pfskip_4
	s_lshl_b32 s16, s12, 12
	s_add_u32 s16, s16, 0x10a00000
	s_lshl_b32 s17, s12, 11
	s_add_u32 s17, s17, 0x18a00000
	s_mul_i32 s18, s12, 0x2400
	s_add_u32 s18, s18, 0x3a00000
	buffer_load_dwordx4 v[8:11], v2, s[60:63], s16 offen
	buffer_load_dwordx4 v[12:15], v2, s[60:63], s16 offen offset:1024
	buffer_load_dwordx4 v[16:19], v2, s[60:63], s17 offen
	buffer_load_dwordx4 v[20:23], v2, s[60:63], s17 offen offset:1024
	buffer_load_dwordx4 v[24:27], v2, s[60:63], s18 offen
	buffer_load_dwordx4 v[28:31], v2, s[60:63], s18 offen offset:1024
	s_branch .Lcmb_pfdone_4

; __device__ __forceinline__ float silu_f(float x) { return x * __builtin_amdgcn_rcpf(1.f + __expf(-x)); }
; __device__ __forceinline__ void ssd_combine_rows(CArgs a, int G) {
;     ...
;     auto finish = [&](int row, const u32x4 (&raw)[6]) {
;         float g[16]; float ss = 0.f;
; #pragma unroll
;         for (int hf = 0; hf < 2; ++hf) {
;             float f[8], bb[8], z[8];
;             unpack8(raw[3 * hf], f); unpack8(raw[3 * hf + 1], bb); unpack8(raw[3 * hf + 2], z);
; #pragma unroll
;             for (int e = 0; e < 8; ++e) { const float y = (f[e] + bb[e]) * silu_f(z[e]); g[8 * hf + e] = y; ss += y * y; }
;         }
;     ...
;     for (int row = gw; row < T; row += 2 * NGW) {
;         const int row2 = row + NGW;
;         u32x4 ra[6], rb[6];
;         load(row, ra);
;         if (row2 < T) load(row2, rb);
;         finish(row, ra);
;         if (row2 < T) finish(row2, rb);
.Lcmb_pfdone_4:
	s_add_i32 s10, s10, s11
	s_cmp_lt_u32 s10, 0x4000
	s_cbranch_scc0 .Lcmb_done
	s_cmp_eq_u32 s22, 0
	s_cbranch_scc1 .Lcmb_wc_5
	s_waitcnt vmcnt(0)
	s_branch .Lcmb_wg_5
.Lcmb_wc_5:
	s_waitcnt vmcnt(14)
.Lcmb_wg_5:
	v_lshlrev_b32_e32 v96, 16, v48
	v_and_b32_e32 v97, 0xffff0000, v48
	v_lshlrev_b32_e32 v98, 16, v49
	v_and_b32_e32 v99, 0xffff0000, v49
	v_lshlrev_b32_e32 v100, 16, v50
	v_and_b32_e32 v101, 0xffff0000, v50
	v_lshlrev_b32_e32 v102, 16, v51
	v_and_b32_e32 v103, 0xffff0000, v51
	v_mul_f32_e32 v104, 0xbfb8aa3b, v96
	v_mul_f32_e32 v105, 0xbfb8aa3b, v97
	v_mul_f32_e32 v106, 0xbfb8aa3b, v98
	v_mul_f32_e32 v107, 0xbfb8aa3b, v99
	v_mul_f32_e32 v108, 0xbfb8aa3b, v100
	v_mul_f32_e32 v109, 0xbfb8aa3b, v101
	v_mul_f32_e32 v110, 0xbfb8aa3b, v102
	v_mul_f32_e32 v111, 0xbfb8aa3b, v103
	v_exp_f32_e32 v104, v104
	v_exp_f32_e32 v105, v105
	v_exp_f32_e32 v106, v106
	v_exp_f32_e32 v107, v107
	v_exp_f32_e32 v108, v108
	v_exp_f32_e32 v109, v109
	v_exp_f32_e32 v110, v110
	v_exp_f32_e32 v111, v111
	v_lshlrev_b32_e32 v112, 16, v32
	v_and_b32_e32 v113, 0xffff0000, v32
	v_lshlrev_b32_e32 v114, 16, v33
	v_and_b32_e32 v115, 0xffff0000, v33
	v_lshlrev_b32_e32 v116, 16, v34
	v_and_b32_e32 v117, 0xffff0000, v34
	v_lshlrev_b32_e32 v118, 16, v35
	v_and_b32_e32 v119, 0xffff0000, v35
	v_lshlrev_b32_e32 v120, 16, v40
	v_and_b32_e32 v121, 0xffff0000, v40
	v_lshlrev_b32_e32 v122, 16, v41
	v_and_b32_e32 v123, 0xffff0000, v41
	v_lshlrev_b32_e32 v124, 16, v42
	v_and_b32_e32 v125, 0xffff0000, v42
	v_lshlrev_b32_e32 v126, 16, v43
	v_and_b32_e32 v127, 0xffff0000, v43
	v_add_f32_e32 v112, v112, v120
	v_add_f32_e32 v113, v113, v121
	v_add_f32_e32 v114, v114, v122
	v_add_f32_e32 v115, v115, v123
	v_add_f32_e32 v116, v116, v124
	v_add_f32_e32 v117, v117, v125
	v_add_f32_e32 v118, v118, v126
	v_add_f32_e32 v119, v119, v127
	v_add_f32_e32 v104, 1.0, v104
	v_add_f32_e32 v105, 1.0, v105
	v_add_f32_e32 v106, 1.0, v106
	v_add_f32_e32 v107, 1.0, v107
	v_add_f32_e32 v108, 1.0, v108
	v_add_f32_e32 v109, 1.0, v109
	v_add_f32_e32 v110, 1.0, v110
	v_add_f32_e32 v111, 1.0, v111
	v_rcp_f32_e32 v104, v104
	v_rcp_f32_e32 v105, v105
	v_rcp_f32_e32 v106, v106
	v_rcp_f32_e32 v107, v107
	v_rcp_f32_e32 v108, v108
	v_rcp_f32_e32 v109, v109
	v_rcp_f32_e32 v110, v110
	v_rcp_f32_e32 v111, v111
	v_mul_f32_e32 v96, v96, v104
	v_mul_f32_e32 v97, v97, v105
	v_mul_f32_e32 v98, v98, v106
	v_mul_f32_e32 v99, v99, v107
	v_mul_f32_e32 v100, v100, v108
	v_mul_f32_e32 v101, v101, v109
	v_mul_f32_e32 v102, v102, v110
	v_mul_f32_e32 v103, v103, v111
	v_mul_f32_e32 v80, v112, v96
	v_mul_f32_e32 v81, v113, v97
	v_mul_f32_e32 v82, v114, v98
	v_mul_f32_e32 v83, v115, v99
	v_mul_f32_e32 v84, v116, v100
	v_mul_f32_e32 v85, v117, v101
	v_mul_f32_e32 v86, v118, v102
	v_mul_f32_e32 v87, v119, v103
	v_mul_f32_e32 v128, v80, v80
	v_fmac_f32_e32 v128, v81, v81
	v_fmac_f32_e32 v128, v82, v82
	v_fmac_f32_e32 v128, v83, v83
	v_fmac_f32_e32 v128, v84, v84
	v_fmac_f32_e32 v128, v85, v85
	v_fmac_f32_e32 v128, v86, v86
	v_fmac_f32_e32 v128, v87, v87
	v_lshlrev_b32_e32 v96, 16, v52
	v_and_b32_e32 v97, 0xffff0000, v52
	v_lshlrev_b32_e32 v98, 16, v53
	v_and_b32_e32 v99, 0xffff0000, v53
	v_lshlrev_b32_e32 v100, 16, v54
	v_and_b32_e32 v101, 0xffff0000, v54
	v_lshlrev_b32_e32 v102, 16, v55
	v_and_b32_e32 v103, 0xffff0000, v55
	v_mul_f32_e32 v104, 0xbfb8aa3b, v96
	v_mul_f32_e32 v105, 0xbfb8aa3b, v97
	v_mul_f32_e32 v106, 0xbfb8aa3b, v98
	v_mul_f32_e32 v107, 0xbfb8aa3b, v99
	v_mul_f32_e32 v108, 0xbfb8aa3b, v100
	v_mul_f32_e32 v109, 0xbfb8aa3b, v101
	v_mul_f32_e32 v110, 0xbfb8aa3b, v102
	v_mul_f32_e32 v111, 0xbfb8aa3b, v103
	v_exp_f32_e32 v104, v104
	v_exp_f32_e32 v105, v105
	v_exp_f32_e32 v106, v106
	v_exp_f32_e32 v107, v107
	v_exp_f32_e32 v108, v108
	v_exp_f32_e32 v109, v109
	v_exp_f32_e32 v110, v110
	v_exp_f32_e32 v111, v111
	v_lshlrev_b32_e32 v112, 16, v36
	v_and_b32_e32 v113, 0xffff0000, v36
	v_lshlrev_b32_e32 v114, 16, v37
	v_and_b32_e32 v115, 0xffff0000, v37
	v_lshlrev_b32_e32 v116, 16, v38
	v_and_b32_e32 v117, 0xffff0000, v38
	v_lshlrev_b32_e32 v118, 16, v39
	v_and_b32_e32 v119, 0xffff0000, v39
	v_lshlrev_b32_e32 v120, 16, v44
	v_and_b32_e32 v121, 0xffff0000, v44
	v_lshlrev_b32_e32 v122, 16, v45
	v_and_b32_e32 v123, 0xffff0000, v45
	v_lshlrev_b32_e32 v124, 16, v46
	v_and_b32_e32 v125, 0xffff0000, v46
	v_lshlrev_b32_e32 v126, 16, v47
	v_and_b32_e32 v127, 0xffff0000, v47
; #define wt16(p, v) wt16b(WSB, (p), (v))
; __device__ __forceinline__ u32x4 pack8(const float (&f)[8]) { u32x4 v; v.x = cvt_pk_bf16(f[0], f[1]); v.y = cvt_pk_bf16(f[2], f[3]); v.z = cvt_pk_bf16(f[4], f[5]); v.w = cvt_pk_bf16(f[6], f[7]); return v; }
; __device__ __forceinline__ void ssd_combine_rows(CArgs a, int G) {
;     ...
;         ss += __shfl_xor(ss, 1); ss += __shfl_xor(ss, 2); ss += __shfl_xor(ss, 4); ss += __shfl_xor(ss, 8); ss += __shfl_xor(ss, 16);
;         const float r = rsqrtf(ss * (1.f / 512.f) + EPS);
;         float o0[8], o1[8];
; #pragma unroll
;         for (int e = 0; e < 8; ++e) { o0[e] = g[e] * r; o1[e] = g[8 + e] * r; }
;         wt16(Y + (size_t)row * 2048 + c0, pack8(o0)); wt16(Y + (size_t)row * 2048 + c0 + 8, pack8(o1));
;     };
;     for (int row = gw; row < T; row += 2 * NGW) {
;         const int row2 = row + NGW;
;         u32x4 ra[6], rb[6];
;         load(row, ra);
;         if (row2 < T) load(row2, rb);
;         finish(row, ra);
;         if (row2 < T) finish(row2, rb);
	v_add_f32_e32 v112, v112, v120
	v_add_f32_e32 v113, v113, v121
	v_add_f32_e32 v114, v114, v122
	v_add_f32_e32 v115, v115, v123
	v_add_f32_e32 v116, v116, v124
	v_add_f32_e32 v117, v117, v125
	v_add_f32_e32 v118, v118, v126
	v_add_f32_e32 v119, v119, v127
	v_add_f32_e32 v104, 1.0, v104
	v_add_f32_e32 v105, 1.0, v105
	v_add_f32_e32 v106, 1.0, v106
	v_add_f32_e32 v107, 1.0, v107
	v_add_f32_e32 v108, 1.0, v108
	v_add_f32_e32 v109, 1.0, v109
	v_add_f32_e32 v110, 1.0, v110
	v_add_f32_e32 v111, 1.0, v111
	v_rcp_f32_e32 v104, v104
	v_rcp_f32_e32 v105, v105
	v_rcp_f32_e32 v106, v106
	v_rcp_f32_e32 v107, v107
	v_rcp_f32_e32 v108, v108
	v_rcp_f32_e32 v109, v109
	v_rcp_f32_e32 v110, v110
	v_rcp_f32_e32 v111, v111
	v_mul_f32_e32 v96, v96, v104
	v_mul_f32_e32 v97, v97, v105
	v_mul_f32_e32 v98, v98, v106
	v_mul_f32_e32 v99, v99, v107
	v_mul_f32_e32 v100, v100, v108
	v_mul_f32_e32 v101, v101, v109
	v_mul_f32_e32 v102, v102, v110
	v_mul_f32_e32 v103, v103, v111
	v_mul_f32_e32 v88, v112, v96
	v_mul_f32_e32 v89, v113, v97
	v_mul_f32_e32 v90, v114, v98
	v_mul_f32_e32 v91, v115, v99
	v_mul_f32_e32 v92, v116, v100
	v_mul_f32_e32 v93, v117, v101
	v_mul_f32_e32 v94, v118, v102
	v_mul_f32_e32 v95, v119, v103
	v_mul_f32_e32 v129, v88, v88
	v_fmac_f32_e32 v129, v89, v89
	v_fmac_f32_e32 v129, v90, v90
	v_fmac_f32_e32 v129, v91, v91
	v_fmac_f32_e32 v129, v92, v92
	v_fmac_f32_e32 v129, v93, v93
	v_fmac_f32_e32 v129, v94, v94
	v_fmac_f32_e32 v129, v95, v95
	s_nop 1
	v_add_f32_dpp v128, v128, v128 row_shr:1 row_mask:0xf bank_mask:0xf bound_ctrl:0
	v_add_f32_dpp v129, v129, v129 row_shr:1 row_mask:0xf bank_mask:0xf bound_ctrl:0
	s_nop 0
	v_add_f32_dpp v128, v128, v128 row_shr:2 row_mask:0xf bank_mask:0xf bound_ctrl:0
	v_add_f32_dpp v129, v129, v129 row_shr:2 row_mask:0xf bank_mask:0xf bound_ctrl:0
	s_nop 0
	v_add_f32_dpp v128, v128, v128 row_shr:4 row_mask:0xf bank_mask:0xf bound_ctrl:0
	v_add_f32_dpp v129, v129, v129 row_shr:4 row_mask:0xf bank_mask:0xf bound_ctrl:0
	s_nop 0
	v_add_f32_dpp v128, v128, v128 row_shr:8 row_mask:0xf bank_mask:0xf bound_ctrl:0
	v_add_f32_dpp v129, v129, v129 row_shr:8 row_mask:0xf bank_mask:0xf bound_ctrl:0
	s_nop 0
	v_add_f32_dpp v128, v128, v128 row_bcast:15 row_mask:0xa bank_mask:0xf
	v_add_f32_dpp v129, v129, v129 row_bcast:15 row_mask:0xa bank_mask:0xf
	s_nop 0
	v_add_f32_dpp v128, v128, v128 row_bcast:31 row_mask:0xc bank_mask:0xf
	v_add_f32_dpp v129, v129, v129 row_bcast:31 row_mask:0xc bank_mask:0xf
	s_nop 0
	s_nop 0
	v_readlane_b32 s20, v128, 63
	v_readlane_b32 s21, v129, 63
	s_nop 1
	v_mov_b32_e32 v130, s20
	v_mov_b32_e32 v131, s21
	v_fmamk_f32 v130, v130, 0x3b000000, v245
	v_fmamk_f32 v131, v131, 0x3b000000, v245
	v_rsq_f32_e32 v130, v130
	v_rsq_f32_e32 v131, v131
	s_nop 0
	v_mul_f32_e32 v80, v80, v130
	v_mul_f32_e32 v81, v81, v130
	v_mul_f32_e32 v82, v82, v130
	v_mul_f32_e32 v83, v83, v130
	v_mul_f32_e32 v84, v84, v130
	v_mul_f32_e32 v85, v85, v130
	v_mul_f32_e32 v86, v86, v130
	v_mul_f32_e32 v87, v87, v130
	v_cvt_pk_bf16_f32 v80, v80, v81
	v_cvt_pk_bf16_f32 v81, v82, v83
	v_cvt_pk_bf16_f32 v82, v84, v85
	v_cvt_pk_bf16_f32 v83, v86, v87
	v_mul_f32_e32 v88, v88, v131
	v_mul_f32_e32 v89, v89, v131
	v_mul_f32_e32 v90, v90, v131
	v_mul_f32_e32 v91, v91, v131
	v_mul_f32_e32 v92, v92, v131
	v_mul_f32_e32 v93, v93, v131
	v_mul_f32_e32 v94, v94, v131
	v_mul_f32_e32 v95, v95, v131
	v_cvt_pk_bf16_f32 v88, v88, v89
	v_cvt_pk_bf16_f32 v89, v90, v91
	v_cvt_pk_bf16_f32 v90, v92, v93
	v_cvt_pk_bf16_f32 v91, v94, v95
	s_lshl_b32 s19, s10, 12
	s_add_u32 s19, s19, 0x10a00000
	buffer_store_dwordx4 v[80:83], v2, s[60:63], s19 offen sc1
	buffer_store_dwordx4 v[88:91], v2, s[60:63], s19 offen offset:1024 sc1
	s_mul_i32 s12, s11, 3
	s_add_i32 s12, s10, s12
	s_cmp_lt_u32 s12, 0x4000
	s_cbranch_scc0 .Lcmb_pfskip_6
	s_lshl_b32 s16, s12, 12
	s_add_u32 s16, s16, 0x10a00000
	s_lshl_b32 s17, s12, 11
	s_add_u32 s17, s17, 0x18a00000
	s_mul_i32 s18, s12, 0x2400
	s_add_u32 s18, s18, 0x3a00000
	buffer_load_dwordx4 v[32:35], v2, s[60:63], s16 offen
	buffer_load_dwordx4 v[36:39], v2, s[60:63], s16 offen offset:1024
	buffer_load_dwordx4 v[40:43], v2, s[60:63], s17 offen
	buffer_load_dwordx4 v[44:47], v2, s[60:63], s17 offen offset:1024
	buffer_load_dwordx4 v[48:51], v2, s[60:63], s18 offen
	buffer_load_dwordx4 v[52:55], v2, s[60:63], s18 offen offset:1024
	s_branch .Lcmb_pfdone_6

; __device__ __forceinline__ float silu_f(float x) { return x * __builtin_amdgcn_rcpf(1.f + __expf(-x)); }
; __device__ __forceinline__ void ssd_combine_rows(CArgs a, int G) {
;     ...
;     auto finish = [&](int row, const u32x4 (&raw)[6]) {
;         float g[16]; float ss = 0.f;
; #pragma unroll
;         for (int hf = 0; hf < 2; ++hf) {
;             float f[8], bb[8], z[8];
;             unpack8(raw[3 * hf], f); unpack8(raw[3 * hf + 1], bb); unpack8(raw[3 * hf + 2], z);
; #pragma unroll
;             for (int e = 0; e < 8; ++e) { const float y = (f[e] + bb[e]) * silu_f(z[e]); g[8 * hf + e] = y; ss += y * y; }
;         }
.Lcmb_wg_7:
	v_lshlrev_b32_e32 v96, 16, v72
	v_and_b32_e32 v97, 0xffff0000, v72
	v_lshlrev_b32_e32 v98, 16, v73
	v_and_b32_e32 v99, 0xffff0000, v73
	v_lshlrev_b32_e32 v100, 16, v74
	v_and_b32_e32 v101, 0xffff0000, v74
	v_lshlrev_b32_e32 v102, 16, v75
	v_and_b32_e32 v103, 0xffff0000, v75
	v_mul_f32_e32 v104, 0xbfb8aa3b, v96
	v_mul_f32_e32 v105, 0xbfb8aa3b, v97
	v_mul_f32_e32 v106, 0xbfb8aa3b, v98
	v_mul_f32_e32 v107, 0xbfb8aa3b, v99
	v_mul_f32_e32 v108, 0xbfb8aa3b, v100
	v_mul_f32_e32 v109, 0xbfb8aa3b, v101
	v_mul_f32_e32 v110, 0xbfb8aa3b, v102
	v_mul_f32_e32 v111, 0xbfb8aa3b, v103
	v_exp_f32_e32 v104, v104
	v_exp_f32_e32 v105, v105
	v_exp_f32_e32 v106, v106
	v_exp_f32_e32 v107, v107
	v_exp_f32_e32 v108, v108
	v_exp_f32_e32 v109, v109
	v_exp_f32_e32 v110, v110
	v_exp_f32_e32 v111, v111
	v_lshlrev_b32_e32 v112, 16, v56
	v_and_b32_e32 v113, 0xffff0000, v56
	v_lshlrev_b32_e32 v114, 16, v57
	v_and_b32_e32 v115, 0xffff0000, v57
	v_lshlrev_b32_e32 v116, 16, v58
	v_and_b32_e32 v117, 0xffff0000, v58
	v_lshlrev_b32_e32 v118, 16, v59
	v_and_b32_e32 v119, 0xffff0000, v59
	v_lshlrev_b32_e32 v120, 16, v64
	v_and_b32_e32 v121, 0xffff0000, v64
	v_lshlrev_b32_e32 v122, 16, v65
	v_and_b32_e32 v123, 0xffff0000, v65
	v_lshlrev_b32_e32 v124, 16, v66
	v_and_b32_e32 v125, 0xffff0000, v66
	v_lshlrev_b32_e32 v126, 16, v67
	v_and_b32_e32 v127, 0xffff0000, v67
	v_add_f32_e32 v112, v112, v120
	v_add_f32_e32 v113, v113, v121
	v_add_f32_e32 v114, v114, v122
	v_add_f32_e32 v115, v115, v123
	v_add_f32_e32 v116, v116, v124
	v_add_f32_e32 v117, v117, v125
	v_add_f32_e32 v118, v118, v126
	v_add_f32_e32 v119, v119, v127
	v_add_f32_e32 v104, 1.0, v104
	v_add_f32_e32 v105, 1.0, v105
	v_add_f32_e32 v106, 1.0, v106
	v_add_f32_e32 v107, 1.0, v107
	v_add_f32_e32 v108, 1.0, v108
	v_add_f32_e32 v109, 1.0, v109
	v_add_f32_e32 v110, 1.0, v110
	v_add_f32_e32 v111, 1.0, v111
	v_rcp_f32_e32 v104, v104
	v_rcp_f32_e32 v105, v105
	v_rcp_f32_e32 v106, v106
	v_rcp_f32_e32 v107, v107
	v_rcp_f32_e32 v108, v108
	v_rcp_f32_e32 v109, v109
	v_rcp_f32_e32 v110, v110
	v_rcp_f32_e32 v111, v111
	v_mul_f32_e32 v96, v96, v104
	v_mul_f32_e32 v97, v97, v105
	v_mul_f32_e32 v98, v98, v106
	v_mul_f32_e32 v99, v99, v107
	v_mul_f32_e32 v100, v100, v108
	v_mul_f32_e32 v101, v101, v109
	v_mul_f32_e32 v102, v102, v110
	v_mul_f32_e32 v103, v103, v111
	v_mul_f32_e32 v80, v112, v96
	v_mul_f32_e32 v81, v113, v97
	v_mul_f32_e32 v82, v114, v98
	v_mul_f32_e32 v83, v115, v99
	v_mul_f32_e32 v84, v116, v100
	v_mul_f32_e32 v85, v117, v101
	v_mul_f32_e32 v86, v118, v102
	v_mul_f32_e32 v87, v119, v103
	v_mul_f32_e32 v128, v80, v80
	v_fmac_f32_e32 v128, v81, v81
	v_fmac_f32_e32 v128, v82, v82
	v_fmac_f32_e32 v128, v83, v83
	v_fmac_f32_e32 v128, v84, v84
	v_fmac_f32_e32 v128, v85, v85
	v_fmac_f32_e32 v128, v86, v86
	v_fmac_f32_e32 v128, v87, v87
	v_lshlrev_b32_e32 v96, 16, v76
	v_and_b32_e32 v97, 0xffff0000, v76
	v_lshlrev_b32_e32 v98, 16, v77
	v_and_b32_e32 v99, 0xffff0000, v77
	v_lshlrev_b32_e32 v100, 16, v78
	v_and_b32_e32 v101, 0xffff0000, v78
	v_lshlrev_b32_e32 v102, 16, v79
	v_and_b32_e32 v103, 0xffff0000, v79
	v_mul_f32_e32 v104, 0xbfb8aa3b, v96
	v_mul_f32_e32 v105, 0xbfb8aa3b, v97
	v_mul_f32_e32 v106, 0xbfb8aa3b, v98
	v_mul_f32_e32 v107, 0xbfb8aa3b, v99
	v_mul_f32_e32 v108, 0xbfb8aa3b, v100
	v_mul_f32_e32 v109, 0xbfb8aa3b, v101
	v_mul_f32_e32 v110, 0xbfb8aa3b, v102
	v_mul_f32_e32 v111, 0xbfb8aa3b, v103
	v_exp_f32_e32 v104, v104
	v_exp_f32_e32 v105, v105
	v_exp_f32_e32 v106, v106
	v_exp_f32_e32 v107, v107
	v_exp_f32_e32 v108, v108
	v_exp_f32_e32 v109, v109
	v_exp_f32_e32 v110, v110
	v_exp_f32_e32 v111, v111
	v_lshlrev_b32_e32 v112, 16, v60
	v_and_b32_e32 v113, 0xffff0000, v60
	v_lshlrev_b32_e32 v114, 16, v61
	v_and_b32_e32 v115, 0xffff0000, v61
	v_lshlrev_b32_e32 v116, 16, v62
	v_and_b32_e32 v117, 0xffff0000, v62
	v_lshlrev_b32_e32 v118, 16, v63
	v_and_b32_e32 v119, 0xffff0000, v63
	v_lshlrev_b32_e32 v120, 16, v68
	v_and_b32_e32 v121, 0xffff0000, v68
	v_lshlrev_b32_e32 v122, 16, v69
	v_and_b32_e32 v123, 0xffff0000, v69
	v_lshlrev_b32_e32 v124, 16, v70
	v_and_b32_e32 v125, 0xffff0000, v70
	v_lshlrev_b32_e32 v126, 16, v71
	v_and_b32_e32 v127, 0xffff0000, v71
	v_add_f32_e32 v112, v112, v120
	v_add_f32_e32 v113, v113, v121
	v_add_f32_e32 v114, v114, v122
; #define wt16(p, v) wt16b(WSB, (p), (v))
; __device__ __forceinline__ u32x4 pack8(const float (&f)[8]) { u32x4 v; v.x = cvt_pk_bf16(f[0], f[1]); v.y = cvt_pk_bf16(f[2], f[3]); v.z = cvt_pk_bf16(f[4], f[5]); v.w = cvt_pk_bf16(f[6], f[7]); return v; }
; __device__ __forceinline__ void ssd_combine_rows(CArgs a, int G) {
;     ...
;         ss += __shfl_xor(ss, 1); ss += __shfl_xor(ss, 2); ss += __shfl_xor(ss, 4); ss += __shfl_xor(ss, 8); ss += __shfl_xor(ss, 16);
;         const float r = rsqrtf(ss * (1.f / 512.f) + EPS);
;         float o0[8], o1[8];
; #pragma unroll
;         for (int e = 0; e < 8; ++e) { o0[e] = g[e] * r; o1[e] = g[8 + e] * r; }
;         wt16(Y + (size_t)row * 2048 + c0, pack8(o0)); wt16(Y + (size_t)row * 2048 + c0 + 8, pack8(o1));
;     };
;     for (int row = gw; row < T; row += 2 * NGW) {
;         const int row2 = row + NGW;
;         u32x4 ra[6], rb[6];
;         load(row, ra);
;         if (row2 < T) load(row2, rb);
;         finish(row, ra);
;         if (row2 < T) finish(row2, rb);
	v_add_f32_e32 v115, v115, v123
	v_add_f32_e32 v116, v116, v124
	v_add_f32_e32 v117, v117, v125
	v_add_f32_e32 v118, v118, v126
	v_add_f32_e32 v119, v119, v127
	v_add_f32_e32 v104, 1.0, v104
	v_add_f32_e32 v105, 1.0, v105
	v_add_f32_e32 v106, 1.0, v106
	v_add_f32_e32 v107, 1.0, v107
	v_add_f32_e32 v108, 1.0, v108
	v_add_f32_e32 v109, 1.0, v109
	v_add_f32_e32 v110, 1.0, v110
	v_add_f32_e32 v111, 1.0, v111
	v_rcp_f32_e32 v104, v104
	v_rcp_f32_e32 v105, v105
	v_rcp_f32_e32 v106, v106
	v_rcp_f32_e32 v107, v107
	v_rcp_f32_e32 v108, v108
	v_rcp_f32_e32 v109, v109
	v_rcp_f32_e32 v110, v110
	v_rcp_f32_e32 v111, v111
	v_mul_f32_e32 v96, v96, v104
	v_mul_f32_e32 v97, v97, v105
	v_mul_f32_e32 v98, v98, v106
	v_mul_f32_e32 v99, v99, v107
	v_mul_f32_e32 v100, v100, v108
	v_mul_f32_e32 v101, v101, v109
	v_mul_f32_e32 v102, v102, v110
	v_mul_f32_e32 v103, v103, v111
	v_mul_f32_e32 v88, v112, v96
	v_mul_f32_e32 v89, v113, v97
	v_mul_f32_e32 v90, v114, v98
	v_mul_f32_e32 v91, v115, v99
	v_mul_f32_e32 v92, v116, v100
	v_mul_f32_e32 v93, v117, v101
	v_mul_f32_e32 v94, v118, v102
	v_mul_f32_e32 v95, v119, v103
	v_mul_f32_e32 v129, v88, v88
	v_fmac_f32_e32 v129, v89, v89
	v_fmac_f32_e32 v129, v90, v90
	v_fmac_f32_e32 v129, v91, v91
	v_fmac_f32_e32 v129, v92, v92
	v_fmac_f32_e32 v129, v93, v93
	v_fmac_f32_e32 v129, v94, v94
	v_fmac_f32_e32 v129, v95, v95
	s_nop 1
	v_add_f32_dpp v128, v128, v128 row_shr:1 row_mask:0xf bank_mask:0xf bound_ctrl:0
	v_add_f32_dpp v129, v129, v129 row_shr:1 row_mask:0xf bank_mask:0xf bound_ctrl:0
	s_nop 0
	v_add_f32_dpp v128, v128, v128 row_shr:2 row_mask:0xf bank_mask:0xf bound_ctrl:0
	v_add_f32_dpp v129, v129, v129 row_shr:2 row_mask:0xf bank_mask:0xf bound_ctrl:0
	s_nop 0
	v_add_f32_dpp v128, v128, v128 row_shr:4 row_mask:0xf bank_mask:0xf bound_ctrl:0
	v_add_f32_dpp v129, v129, v129 row_shr:4 row_mask:0xf bank_mask:0xf bound_ctrl:0
	s_nop 0
	v_add_f32_dpp v128, v128, v128 row_shr:8 row_mask:0xf bank_mask:0xf bound_ctrl:0
	v_add_f32_dpp v129, v129, v129 row_shr:8 row_mask:0xf bank_mask:0xf bound_ctrl:0
	s_nop 0
	v_add_f32_dpp v128, v128, v128 row_bcast:15 row_mask:0xa bank_mask:0xf
	v_add_f32_dpp v129, v129, v129 row_bcast:15 row_mask:0xa bank_mask:0xf
	s_nop 0
	v_add_f32_dpp v128, v128, v128 row_bcast:31 row_mask:0xc bank_mask:0xf
	v_add_f32_dpp v129, v129, v129 row_bcast:31 row_mask:0xc bank_mask:0xf
	s_nop 0
	s_nop 0
	v_readlane_b32 s20, v128, 63
	v_readlane_b32 s21, v129, 63
	s_nop 1
	v_mov_b32_e32 v130, s20
	v_mov_b32_e32 v131, s21
	v_fmamk_f32 v130, v130, 0x3b000000, v245
	v_fmamk_f32 v131, v131, 0x3b000000, v245
	v_rsq_f32_e32 v130, v130
	v_rsq_f32_e32 v131, v131
	s_nop 0
	v_mul_f32_e32 v80, v80, v130
	v_mul_f32_e32 v81, v81, v130
	v_mul_f32_e32 v82, v82, v130
	v_mul_f32_e32 v83, v83, v130
	v_mul_f32_e32 v84, v84, v130
	v_mul_f32_e32 v85, v85, v130
	v_mul_f32_e32 v86, v86, v130
	v_mul_f32_e32 v87, v87, v130
	v_cvt_pk_bf16_f32 v80, v80, v81
	v_cvt_pk_bf16_f32 v81, v82, v83
	v_cvt_pk_bf16_f32 v82, v84, v85
	v_cvt_pk_bf16_f32 v83, v86, v87
	v_mul_f32_e32 v88, v88, v131
	v_mul_f32_e32 v89, v89, v131
	v_mul_f32_e32 v90, v90, v131
	v_mul_f32_e32 v91, v91, v131
	v_mul_f32_e32 v92, v92, v131
	v_mul_f32_e32 v93, v93, v131
	v_mul_f32_e32 v94, v94, v131
	v_mul_f32_e32 v95, v95, v131
	v_cvt_pk_bf16_f32 v88, v88, v89
	v_cvt_pk_bf16_f32 v89, v90, v91
	v_cvt_pk_bf16_f32 v90, v92, v93
	v_cvt_pk_bf16_f32 v91, v94, v95
	s_lshl_b32 s19, s10, 12
	s_add_u32 s19, s19, 0x10a00000
	buffer_store_dwordx4 v[80:83], v2, s[60:63], s19 offen sc1
	buffer_store_dwordx4 v[88:91], v2, s[60:63], s19 offen offset:1024 sc1
	s_mul_i32 s12, s11, 3
	s_add_i32 s12, s10, s12
	s_cmp_lt_u32 s12, 0x4000
	s_cbranch_scc0 .Lcmb_pfskip_8
	s_lshl_b32 s16, s12, 12
	s_add_u32 s16, s16, 0x10a00000
	s_lshl_b32 s17, s12, 11
	s_add_u32 s17, s17, 0x18a00000
	s_mul_i32 s18, s12, 0x2400
	s_add_u32 s18, s18, 0x3a00000
	buffer_load_dwordx4 v[56:59], v2, s[60:63], s16 offen
	buffer_load_dwordx4 v[60:63], v2, s[60:63], s16 offen offset:1024
	buffer_load_dwordx4 v[64:67], v2, s[60:63], s17 offen
	buffer_load_dwordx4 v[68:71], v2, s[60:63], s17 offen offset:1024
	buffer_load_dwordx4 v[72:75], v2, s[60:63], s18 offen
	buffer_load_dwordx4 v[76:79], v2, s[60:63], s18 offen offset:1024
	s_branch .Lcmb_pfdone_8

; __device__ __forceinline__ void ssd_combine_rows(CArgs a, int G) {
;     ...
;     for (int row = gw; row < T; row += 2 * NGW) {
;         const int row2 = row + NGW;
;         u32x4 ra[6], rb[6];
;         load(row, ra);
;         if (row2 < T) load(row2, rb);
;         finish(row, ra);
;         if (row2 < T) finish(row2, rb);
.Lcmb_pfdone_8:
	s_add_i32 s10, s10, s11
	s_cmp_lt_u32 s10, 0x4000
	s_cbranch_scc0 .Lcmb_done

; __device__ __forceinline__ void ssd_combine_rows(CArgs a, int G) {
;     ...
;     for (int row = gw; row < T; row += 2 * NGW) {
;         const int row2 = row + NGW;
;         u32x4 ra[6], rb[6];
;         load(row, ra);
;         if (row2 < T) load(row2, rb);
;         finish(row, ra);
;         if (row2 < T) finish(row2, rb);
.Lcmb_pfdone_14:
	s_add_i32 s10, s10, s11
	s_cmp_lt_u32 s10, 0x4000
	s_cbranch_scc0 .Lcmb_done
	s_branch .Lcmb_loop

; __device__ __forceinline__ int ltid() { int t = threadIdx.x; asm volatile("" : "+v"(t)); return t; }
; __device__ __forceinline__ int lbid() { int t = blockIdx.x; asm volatile("" : "+s"(t)); return t; }
; __device__ __forceinline__ void conv_mixer_rows(CArgs a, int layer, int G) {
;     const int lane = ltid() & 63, wave = ltid() >> 6;
;     const int gw = lbid() * NWAVES + wave, NGW = G * NWAVES;
;     const unsigned char* WSB = a->ws;
;     const bf16_t* U = (const bf16_t*)(a->ws + WS_U); bf16_t* Y = (bf16_t*)(a->ws + WS_Y);
;     const float* cw = a->conv_w + (size_t)layer * 3 * 512;
;     const int c0 = lane * 8;
;     float w[3][8];
; #pragma unroll
;     for (int k = 0; k < 3; ++k) { const f32x4 a0 = *(const f32x4*)(cw + k * 512 + c0), a1 = *(const f32x4*)(cw + k * 512 + c0 + 4);
;         w[k][0] = a0[0]; w[k][1] = a0[1]; w[k][2] = a0[2]; w[k][3] = a0[3]; w[k][4] = a1[0]; w[k][5] = a1[1]; w[k][6] = a1[2]; w[k][7] = a1[3]; }
;     auto load = [&](int row, u32x4 (&raw)[7]) {
;         const int s = row & (SEQ - 1);
; #pragma unroll
;         for (int k = 0; k < 3; ++k) {
;             const int sp = s + k - 1; const int rr = (sp >= 0 && sp < SEQ) ? row + k - 1 : row;
;             const bf16_t* ur = U + (size_t)rr * NU;
;             u32x4 h = *(const u32x4*)(ur + UCH + c0), c = *(const u32x4*)(ur + UCC + c0);
;             if (!(sp >= 0 && sp < SEQ)) { h = (u32x4){0u, 0u, 0u, 0u}; c = (u32x4){0u, 0u, 0u, 0u}; }
;             raw[2 * k] = h; raw[2 * k + 1] = c;
;         }
;         raw[6] = *(const u32x4*)(U + (size_t)row * NU + UCB + c0);
;     };
;     ...
;     for (int row = gw; row < T; row += 2 * NGW) {
;         const int row2 = row + NGW;
;         u32x4 ra[7], rb[7];
;         load(row, ra);
;         if (row2 < T) load(row2, rb);
.Lcvm_map:
	s_lshl_b32 s17, s17, 3
	s_add_i32 s10, s10, s17
	s_mul_i32 s17, s8, 0x1800
	s_waitcnt lgkmcnt(0)
	s_and_b32 s61, s61, 0xffff
	s_add_u32 s12, s12, s17
	s_addc_u32 s13, s13, 0
	s_cmp_lt_u32 s10, 0x4000
	s_cbranch_scc0 .Lcvm_done
	global_load_dwordx4 v[8:11], v6, s[12:13]
	global_load_dwordx4 v[12:15], v6, s[12:13] offset:16
	global_load_dwordx4 v[16:19], v6, s[12:13] offset:2048
	global_load_dwordx4 v[20:23], v6, s[12:13] offset:2064
	s_add_u32 s12, s12, 0x1000
	s_addc_u32 s13, s13, 0
	global_load_dwordx4 v[24:27], v6, s[12:13]
	global_load_dwordx4 v[28:31], v6, s[12:13] offset:16
	s_mov_b32 s23, 0
	s_and_b32 s21, s10, 0x7ff
	s_mul_i32 s19, s10, 0x2400
	s_add_u32 s19, s19, 0x3a00000
	s_sub_u32 s18, s19, 0x2400
	s_add_u32 s20, s19, 0x2400
	s_cmp_eq_u32 s21, 0
	s_cselect_b32 s18, s19, s18
	s_cmpk_eq_u32 s21, 0x7ff
	s_cselect_b32 s20, s19, s20
	buffer_load_dwordx4 v[32:35], v2, s[60:63], s18 offen
	buffer_load_dwordx4 v[36:39], v3, s[60:63], s18 offen
	buffer_load_dwordx4 v[40:43], v2, s[60:63], s19 offen
	buffer_load_dwordx4 v[44:47], v3, s[60:63], s19 offen
	buffer_load_dwordx4 v[48:51], v4, s[60:63], s19 offen
	buffer_load_dwordx4 v[52:55], v2, s[60:63], s20 offen
	buffer_load_dwordx4 v[56:59], v3, s[60:63], s20 offen
	s_mul_i32 s17, s16, 1
	s_add_i32 s17, s10, s17
	s_cmp_lt_u32 s17, 0x4000
	s_cbranch_scc0 .Lcvm_pfskip_1
	s_and_b32 s21, s17, 0x7ff
	s_mul_i32 s19, s17, 0x2400
	s_add_u32 s19, s19, 0x3a00000
	s_sub_u32 s18, s19, 0x2400
	s_add_u32 s20, s19, 0x2400
	s_cmp_eq_u32 s21, 0
	s_cselect_b32 s18, s19, s18
	s_cmpk_eq_u32 s21, 0x7ff
	s_cselect_b32 s20, s19, s20
	buffer_load_dwordx4 v[60:63], v2, s[60:63], s18 offen
	buffer_load_dwordx4 v[64:67], v3, s[60:63], s18 offen
	buffer_load_dwordx4 v[68:71], v2, s[60:63], s19 offen
	buffer_load_dwordx4 v[72:75], v3, s[60:63], s19 offen
	buffer_load_dwordx4 v[76:79], v4, s[60:63], s19 offen
	buffer_load_dwordx4 v[80:83], v2, s[60:63], s20 offen
	buffer_load_dwordx4 v[84:87], v3, s[60:63], s20 offen
	s_branch .Lcvm_pfdone_1
.Lcvm_pfskip_1:
	s_mov_b32 s23, 1
.Lcvm_pfdone_1:
	s_mul_i32 s17, s16, 2
	s_add_i32 s17, s10, s17
	s_cmp_lt_u32 s17, 0x4000
	s_cbranch_scc0 .Lcvm_pfskip_2
	s_and_b32 s21, s17, 0x7ff
	s_mul_i32 s19, s17, 0x2400
	s_add_u32 s19, s19, 0x3a00000
	s_sub_u32 s18, s19, 0x2400
	s_add_u32 s20, s19, 0x2400
	s_cmp_eq_u32 s21, 0
	s_cselect_b32 s18, s19, s18
	s_cmpk_eq_u32 s21, 0x7ff
	s_cselect_b32 s20, s19, s20
	buffer_load_dwordx4 v[88:91], v2, s[60:63], s18 offen
	buffer_load_dwordx4 v[92:95], v3, s[60:63], s18 offen
	buffer_load_dwordx4 v[96:99], v2, s[60:63], s19 offen
	buffer_load_dwordx4 v[100:103], v3, s[60:63], s19 offen
	buffer_load_dwordx4 v[104:107], v4, s[60:63], s19 offen
	buffer_load_dwordx4 v[108:111], v2, s[60:63], s20 offen
	buffer_load_dwordx4 v[112:115], v3, s[60:63], s20 offen
	s_branch .Lcvm_pfdone_2

; __device__ __forceinline__ void conv_mixer_rows(CArgs a, int layer, int G) {
;     ...
;     for (int row = gw; row < T; row += 2 * NGW) {
;         const int row2 = row + NGW;
;         u32x4 ra[7], rb[7];
;         load(row, ra);
;         if (row2 < T) load(row2, rb);
;         finish(row, ra);
.Lcvm_pfdone_2:
	s_cmp_eq_u32 s23, 0
	s_cbranch_scc1 .Lcvm_wc_3
	s_waitcnt vmcnt(0)
	s_branch .Lcvm_wg_3

; __device__ __forceinline__ void conv_mixer_rows(CArgs a, int layer, int G) {
;     ...
;     auto load = [&](int row, u32x4 (&raw)[7]) {
;         const int s = row & (SEQ - 1);
; #pragma unroll
;         for (int k = 0; k < 3; ++k) {
;             const int sp = s + k - 1; const int rr = (sp >= 0 && sp < SEQ) ? row + k - 1 : row;
;             const bf16_t* ur = U + (size_t)rr * NU;
;             u32x4 h = *(const u32x4*)(ur + UCH + c0), c = *(const u32x4*)(ur + UCC + c0);
;             if (!(sp >= 0 && sp < SEQ)) { h = (u32x4){0u, 0u, 0u, 0u}; c = (u32x4){0u, 0u, 0u, 0u}; }
;             raw[2 * k] = h; raw[2 * k + 1] = c;
;         }
;         raw[6] = *(const u32x4*)(U + (size_t)row * NU + UCB + c0);
;     };
.Lcvm_wg_3:
	s_and_b32 s21, s10, 0x7ff
	s_cmp_lg_u32 s21, 0
	s_cbranch_scc1 .Lcvm_nz0_1
	v_mov_b32_e32 v32, 0
	v_mov_b32_e32 v33, 0
	v_mov_b32_e32 v34, 0
	v_mov_b32_e32 v35, 0

; #define wt16(p, v) wt16b(WSB, (p), (v))
; __device__ __forceinline__ u32x4 pack8(const float (&f)[8]) { u32x4 v; v.x = cvt_pk_bf16(f[0], f[1]); v.y = cvt_pk_bf16(f[2], f[3]); v.z = cvt_pk_bf16(f[4], f[5]); v.w = cvt_pk_bf16(f[6], f[7]); return v; }
; __device__ __forceinline__ void conv_mixer_rows(CArgs a, int layer, int G) {
;     ...
;     auto finish = [&](int row, const u32x4 (&raw)[7]) {
;         float accv[8];
; #pragma unroll
;         for (int e = 0; e < 8; ++e) accv[e] = 0.f;
; #pragma unroll
;         for (int k = 0; k < 3; ++k) { float ch[8], cc[8]; unpack8(raw[2 * k], ch); unpack8(raw[2 * k + 1], cc);
; #pragma unroll
;             for (int e = 0; e < 8; ++e) accv[e] += w[k][e] * (cc[e] * ch[e]); }
;         float cbv[8]; unpack8(raw[6], cbv);
;         float ss = 0.f;
; #pragma unroll
;         for (int e = 0; e < 8; ++e) { accv[e] *= cbv[e]; ss += accv[e] * accv[e]; }
;         ss += __shfl_xor(ss, 1); ss += __shfl_xor(ss, 2); ss += __shfl_xor(ss, 4);
;         const float r = rsqrtf(ss * (1.f / 64.f) + EPS);
; #pragma unroll
;         for (int e = 0; e < 8; ++e) accv[e] *= r;
;         wt16(Y + (size_t)row * 2048 + 1536 + c0, pack8(accv));
;     };
;     for (int row = gw; row < T; row += 2 * NGW) {
;         const int row2 = row + NGW;
;         u32x4 ra[7], rb[7];
;         load(row, ra);
;         if (row2 < T) load(row2, rb);
;         finish(row, ra);
;         if (row2 < T) finish(row2, rb);
;     }
.Lcvm_nz2_1:
	v_lshlrev_b32_e32 v128, 16, v32
	v_and_b32_e32 v129, 0xffff0000, v32
	v_lshlrev_b32_e32 v130, 16, v33
	v_and_b32_e32 v131, 0xffff0000, v33
	v_lshlrev_b32_e32 v132, 16, v34
	v_and_b32_e32 v133, 0xffff0000, v34
	v_lshlrev_b32_e32 v134, 16, v35
	v_and_b32_e32 v135, 0xffff0000, v35
	v_lshlrev_b32_e32 v136, 16, v36
	v_and_b32_e32 v137, 0xffff0000, v36
	v_lshlrev_b32_e32 v138, 16, v37
	v_and_b32_e32 v139, 0xffff0000, v37
	v_lshlrev_b32_e32 v140, 16, v38
	v_and_b32_e32 v141, 0xffff0000, v38
	v_lshlrev_b32_e32 v142, 16, v39
	v_and_b32_e32 v143, 0xffff0000, v39
	v_mul_f32_e32 v128, v136, v128
	v_mul_f32_e32 v129, v137, v129
	v_mul_f32_e32 v130, v138, v130
	v_mul_f32_e32 v131, v139, v131
	v_mul_f32_e32 v132, v140, v132
	v_mul_f32_e32 v133, v141, v133
	v_mul_f32_e32 v134, v142, v134
	v_mul_f32_e32 v135, v143, v135
	v_mul_f32_e32 v120, v8, v128
	v_mul_f32_e32 v121, v9, v129
	v_mul_f32_e32 v122, v10, v130
	v_mul_f32_e32 v123, v11, v131
	v_mul_f32_e32 v124, v12, v132
	v_mul_f32_e32 v125, v13, v133
	v_mul_f32_e32 v126, v14, v134
	v_mul_f32_e32 v127, v15, v135
	v_lshlrev_b32_e32 v128, 16, v40
	v_and_b32_e32 v129, 0xffff0000, v40
	v_lshlrev_b32_e32 v130, 16, v41
	v_and_b32_e32 v131, 0xffff0000, v41
	v_lshlrev_b32_e32 v132, 16, v42
	v_and_b32_e32 v133, 0xffff0000, v42
	v_lshlrev_b32_e32 v134, 16, v43
	v_and_b32_e32 v135, 0xffff0000, v43
	v_lshlrev_b32_e32 v136, 16, v44
	v_and_b32_e32 v137, 0xffff0000, v44
	v_lshlrev_b32_e32 v138, 16, v45
	v_and_b32_e32 v139, 0xffff0000, v45
	v_lshlrev_b32_e32 v140, 16, v46
	v_and_b32_e32 v141, 0xffff0000, v46
	v_lshlrev_b32_e32 v142, 16, v47
	v_and_b32_e32 v143, 0xffff0000, v47
	v_mul_f32_e32 v128, v136, v128
	v_mul_f32_e32 v129, v137, v129
	v_mul_f32_e32 v130, v138, v130
	v_mul_f32_e32 v131, v139, v131
	v_mul_f32_e32 v132, v140, v132
	v_mul_f32_e32 v133, v141, v133
	v_mul_f32_e32 v134, v142, v134
	v_mul_f32_e32 v135, v143, v135
	v_fmac_f32_e32 v120, v16, v128
	v_fmac_f32_e32 v121, v17, v129
	v_fmac_f32_e32 v122, v18, v130
	v_fmac_f32_e32 v123, v19, v131
	v_fmac_f32_e32 v124, v20, v132
	v_fmac_f32_e32 v125, v21, v133
	v_fmac_f32_e32 v126, v22, v134
	v_fmac_f32_e32 v127, v23, v135
	v_lshlrev_b32_e32 v128, 16, v52
	v_and_b32_e32 v129, 0xffff0000, v52
	v_lshlrev_b32_e32 v130, 16, v53
	v_and_b32_e32 v131, 0xffff0000, v53
	v_lshlrev_b32_e32 v132, 16, v54
	v_and_b32_e32 v133, 0xffff0000, v54
	v_lshlrev_b32_e32 v134, 16, v55
	v_and_b32_e32 v135, 0xffff0000, v55
	v_lshlrev_b32_e32 v136, 16, v56
	v_and_b32_e32 v137, 0xffff0000, v56
	v_lshlrev_b32_e32 v138, 16, v57
	v_and_b32_e32 v139, 0xffff0000, v57
	v_lshlrev_b32_e32 v140, 16, v58
	v_and_b32_e32 v141, 0xffff0000, v58
	v_lshlrev_b32_e32 v142, 16, v59
	v_and_b32_e32 v143, 0xffff0000, v59
	v_mul_f32_e32 v128, v136, v128
	v_mul_f32_e32 v129, v137, v129
	v_mul_f32_e32 v130, v138, v130
	v_mul_f32_e32 v131, v139, v131
	v_mul_f32_e32 v132, v140, v132
	v_mul_f32_e32 v133, v141, v133
	v_mul_f32_e32 v134, v142, v134
	v_mul_f32_e32 v135, v143, v135
	v_fmac_f32_e32 v120, v24, v128
	v_fmac_f32_e32 v121, v25, v129
	v_fmac_f32_e32 v122, v26, v130
	v_fmac_f32_e32 v123, v27, v131
	v_fmac_f32_e32 v124, v28, v132
	v_fmac_f32_e32 v125, v29, v133
	v_fmac_f32_e32 v126, v30, v134
	v_fmac_f32_e32 v127, v31, v135
	v_lshlrev_b32_e32 v136, 16, v48
	v_and_b32_e32 v137, 0xffff0000, v48
	v_lshlrev_b32_e32 v138, 16, v49
	v_and_b32_e32 v139, 0xffff0000, v49
	v_lshlrev_b32_e32 v140, 16, v50
	v_and_b32_e32 v141, 0xffff0000, v50
	v_lshlrev_b32_e32 v142, 16, v51
	v_and_b32_e32 v143, 0xffff0000, v51
	v_mul_f32_e32 v120, v120, v136
	v_mul_f32_e32 v121, v121, v137
	v_mul_f32_e32 v122, v122, v138
	v_mul_f32_e32 v123, v123, v139
	v_mul_f32_e32 v124, v124, v140
	v_mul_f32_e32 v125, v125, v141
	v_mul_f32_e32 v126, v126, v142
	v_mul_f32_e32 v127, v127, v143
	v_mul_f32_e32 v144, v120, v120
	v_fmac_f32_e32 v144, v121, v121
	v_fmac_f32_e32 v144, v122, v122
	v_fmac_f32_e32 v144, v123, v123
	v_fmac_f32_e32 v144, v124, v124
	v_fmac_f32_e32 v144, v125, v125
	v_fmac_f32_e32 v144, v126, v126
	v_fmac_f32_e32 v144, v127, v127
	s_nop 1
	v_add_f32_dpp v144, v144, v144 quad_perm:[1,0,3,2] row_mask:0xf bank_mask:0xf
	s_nop 1
	v_add_f32_dpp v144, v144, v144 quad_perm:[2,3,0,1] row_mask:0xf bank_mask:0xf
	s_nop 1
	v_add_f32_dpp v144, v144, v144 row_half_mirror row_mask:0xf bank_mask:0xf
	v_fmamk_f32 v145, v144, 0x3c800000, v245
	v_rsq_f32_e32 v145, v145
	s_lshl_b32 s22, s10, 12
	s_add_u32 s22, s22, 0x10a00000
	v_mul_f32_e32 v120, v120, v145
	v_mul_f32_e32 v121, v121, v145
	v_mul_f32_e32 v122, v122, v145
	v_mul_f32_e32 v123, v123, v145
	v_mul_f32_e32 v124, v124, v145
	v_mul_f32_e32 v125, v125, v145
	v_mul_f32_e32 v126, v126, v145
	v_mul_f32_e32 v127, v127, v145
	v_cvt_pk_bf16_f32 v120, v120, v121
	v_cvt_pk_bf16_f32 v121, v122, v123
	v_cvt_pk_bf16_f32 v122, v124, v125
	v_cvt_pk_bf16_f32 v123, v126, v127
	buffer_store_dwordx4 v[120:123], v5, s[60:63], s22 offen sc1
	s_mul_i32 s17, s16, 3
	s_add_i32 s17, s10, s17
	s_cmp_lt_u32 s17, 0x4000
	s_cbranch_scc0 .Lcvm_pfskip_4
	s_and_b32 s21, s17, 0x7ff
	s_mul_i32 s19, s17, 0x2400
	s_add_u32 s19, s19, 0x3a00000
	s_sub_u32 s18, s19, 0x2400
	s_add_u32 s20, s19, 0x2400
	s_cmp_eq_u32 s21, 0
	s_cselect_b32 s18, s19, s18
	s_cmpk_eq_u32 s21, 0x7ff
	s_cselect_b32 s20, s19, s20
	buffer_load_dwordx4 v[32:35], v2, s[60:63], s18 offen
	buffer_load_dwordx4 v[36:39], v3, s[60:63], s18 offen
	buffer_load_dwordx4 v[40:43], v2, s[60:63], s19 offen
	buffer_load_dwordx4 v[44:47], v3, s[60:63], s19 offen
	buffer_load_dwordx4 v[48:51], v4, s[60:63], s19 offen
	buffer_load_dwordx4 v[52:55], v2, s[60:63], s20 offen
	buffer_load_dwordx4 v[56:59], v3, s[60:63], s20 offen
	s_branch .Lcvm_pfdone_4

; __device__ __forceinline__ void conv_mixer_rows(CArgs a, int layer, int G) {
;     ...
;     for (int row = gw; row < T; row += 2 * NGW) {
;         const int row2 = row + NGW;
;         u32x4 ra[7], rb[7];
;         load(row, ra);
;         if (row2 < T) load(row2, rb);
;         finish(row, ra);
;         if (row2 < T) finish(row2, rb);
;     }
.Lcvm_pfdone_4:
	s_add_i32 s10, s10, s16
	s_cmp_lt_u32 s10, 0x4000
	s_cbranch_scc0 .Lcvm_done
	s_cmp_eq_u32 s23, 0
	s_cbranch_scc1 .Lcvm_wc_5
	s_waitcnt vmcnt(0)
	s_branch .Lcvm_wg_5
.Lcvm_wc_5:
	s_waitcnt vmcnt(15)
.Lcvm_wg_5:
	s_and_b32 s21, s10, 0x7ff
	s_cmp_lg_u32 s21, 0
	s_cbranch_scc1 .Lcvm_nz0_2
	v_mov_b32_e32 v60, 0
	v_mov_b32_e32 v61, 0
	v_mov_b32_e32 v62, 0
	v_mov_b32_e32 v63, 0

; #define wt16(p, v) wt16b(WSB, (p), (v))
; __device__ __forceinline__ u32x4 pack8(const float (&f)[8]) { u32x4 v; v.x = cvt_pk_bf16(f[0], f[1]); v.y = cvt_pk_bf16(f[2], f[3]); v.z = cvt_pk_bf16(f[4], f[5]); v.w = cvt_pk_bf16(f[6], f[7]); return v; }
; __device__ __forceinline__ void conv_mixer_rows(CArgs a, int layer, int G) {
;     ...
;     auto finish = [&](int row, const u32x4 (&raw)[7]) {
;         float accv[8];
; #pragma unroll
;         for (int e = 0; e < 8; ++e) accv[e] = 0.f;
; #pragma unroll
;         for (int k = 0; k < 3; ++k) { float ch[8], cc[8]; unpack8(raw[2 * k], ch); unpack8(raw[2 * k + 1], cc);
; #pragma unroll
;             for (int e = 0; e < 8; ++e) accv[e] += w[k][e] * (cc[e] * ch[e]); }
;         float cbv[8]; unpack8(raw[6], cbv);
;         float ss = 0.f;
; #pragma unroll
;         for (int e = 0; e < 8; ++e) { accv[e] *= cbv[e]; ss += accv[e] * accv[e]; }
;         ss += __shfl_xor(ss, 1); ss += __shfl_xor(ss, 2); ss += __shfl_xor(ss, 4);
;         const float r = rsqrtf(ss * (1.f / 64.f) + EPS);
; #pragma unroll
;         for (int e = 0; e < 8; ++e) accv[e] *= r;
;         wt16(Y + (size_t)row * 2048 + 1536 + c0, pack8(accv));
;     };
;     for (int row = gw; row < T; row += 2 * NGW) {
;         const int row2 = row + NGW;
;         u32x4 ra[7], rb[7];
;         load(row, ra);
;         if (row2 < T) load(row2, rb);
;         finish(row, ra);
;         if (row2 < T) finish(row2, rb);
;     }
.Lcvm_nz2_2:
	v_lshlrev_b32_e32 v128, 16, v60
	v_and_b32_e32 v129, 0xffff0000, v60
	v_lshlrev_b32_e32 v130, 16, v61
	v_and_b32_e32 v131, 0xffff0000, v61
	v_lshlrev_b32_e32 v132, 16, v62
	v_and_b32_e32 v133, 0xffff0000, v62
	v_lshlrev_b32_e32 v134, 16, v63
	v_and_b32_e32 v135, 0xffff0000, v63
	v_lshlrev_b32_e32 v136, 16, v64
	v_and_b32_e32 v137, 0xffff0000, v64
	v_lshlrev_b32_e32 v138, 16, v65
	v_and_b32_e32 v139, 0xffff0000, v65
	v_lshlrev_b32_e32 v140, 16, v66
	v_and_b32_e32 v141, 0xffff0000, v66
	v_lshlrev_b32_e32 v142, 16, v67
	v_and_b32_e32 v143, 0xffff0000, v67
	v_mul_f32_e32 v128, v136, v128
	v_mul_f32_e32 v129, v137, v129
	v_mul_f32_e32 v130, v138, v130
	v_mul_f32_e32 v131, v139, v131
	v_mul_f32_e32 v132, v140, v132
	v_mul_f32_e32 v133, v141, v133
	v_mul_f32_e32 v134, v142, v134
	v_mul_f32_e32 v135, v143, v135
	v_mul_f32_e32 v120, v8, v128
	v_mul_f32_e32 v121, v9, v129
	v_mul_f32_e32 v122, v10, v130
	v_mul_f32_e32 v123, v11, v131
	v_mul_f32_e32 v124, v12, v132
	v_mul_f32_e32 v125, v13, v133
	v_mul_f32_e32 v126, v14, v134
	v_mul_f32_e32 v127, v15, v135
	v_lshlrev_b32_e32 v128, 16, v68
	v_and_b32_e32 v129, 0xffff0000, v68
	v_lshlrev_b32_e32 v130, 16, v69
	v_and_b32_e32 v131, 0xffff0000, v69
	v_lshlrev_b32_e32 v132, 16, v70
	v_and_b32_e32 v133, 0xffff0000, v70
	v_lshlrev_b32_e32 v134, 16, v71
	v_and_b32_e32 v135, 0xffff0000, v71
	v_lshlrev_b32_e32 v136, 16, v72
	v_and_b32_e32 v137, 0xffff0000, v72
	v_lshlrev_b32_e32 v138, 16, v73
	v_and_b32_e32 v139, 0xffff0000, v73
	v_lshlrev_b32_e32 v140, 16, v74
	v_and_b32_e32 v141, 0xffff0000, v74
	v_lshlrev_b32_e32 v142, 16, v75
	v_and_b32_e32 v143, 0xffff0000, v75
	v_mul_f32_e32 v128, v136, v128
	v_mul_f32_e32 v129, v137, v129
	v_mul_f32_e32 v130, v138, v130
	v_mul_f32_e32 v131, v139, v131
	v_mul_f32_e32 v132, v140, v132
	v_mul_f32_e32 v133, v141, v133
	v_mul_f32_e32 v134, v142, v134
	v_mul_f32_e32 v135, v143, v135
	v_fmac_f32_e32 v120, v16, v128
	v_fmac_f32_e32 v121, v17, v129
	v_fmac_f32_e32 v122, v18, v130
	v_fmac_f32_e32 v123, v19, v131
	v_fmac_f32_e32 v124, v20, v132
	v_fmac_f32_e32 v125, v21, v133
	v_fmac_f32_e32 v126, v22, v134
	v_fmac_f32_e32 v127, v23, v135
	v_lshlrev_b32_e32 v128, 16, v80
	v_and_b32_e32 v129, 0xffff0000, v80
	v_lshlrev_b32_e32 v130, 16, v81
	v_and_b32_e32 v131, 0xffff0000, v81
	v_lshlrev_b32_e32 v132, 16, v82
	v_and_b32_e32 v133, 0xffff0000, v82
	v_lshlrev_b32_e32 v134, 16, v83
	v_and_b32_e32 v135, 0xffff0000, v83
	v_lshlrev_b32_e32 v136, 16, v84
	v_and_b32_e32 v137, 0xffff0000, v84
	v_lshlrev_b32_e32 v138, 16, v85
	v_and_b32_e32 v139, 0xffff0000, v85
	v_lshlrev_b32_e32 v140, 16, v86
	v_and_b32_e32 v141, 0xffff0000, v86
	v_lshlrev_b32_e32 v142, 16, v87
	v_and_b32_e32 v143, 0xffff0000, v87
	v_mul_f32_e32 v128, v136, v128
	v_mul_f32_e32 v129, v137, v129
	v_mul_f32_e32 v130, v138, v130
	v_mul_f32_e32 v131, v139, v131
	v_mul_f32_e32 v132, v140, v132
	v_mul_f32_e32 v133, v141, v133
	v_mul_f32_e32 v134, v142, v134
	v_mul_f32_e32 v135, v143, v135
	v_fmac_f32_e32 v120, v24, v128
	v_fmac_f32_e32 v121, v25, v129
	v_fmac_f32_e32 v122, v26, v130
	v_fmac_f32_e32 v123, v27, v131
	v_fmac_f32_e32 v124, v28, v132
	v_fmac_f32_e32 v125, v29, v133
	v_fmac_f32_e32 v126, v30, v134
	v_fmac_f32_e32 v127, v31, v135
	v_lshlrev_b32_e32 v136, 16, v76
	v_and_b32_e32 v137, 0xffff0000, v76
	v_lshlrev_b32_e32 v138, 16, v77
	v_and_b32_e32 v139, 0xffff0000, v77
	v_lshlrev_b32_e32 v140, 16, v78
	v_and_b32_e32 v141, 0xffff0000, v78
	v_lshlrev_b32_e32 v142, 16, v79
	v_and_b32_e32 v143, 0xffff0000, v79
	v_mul_f32_e32 v120, v120, v136
	v_mul_f32_e32 v121, v121, v137
	v_mul_f32_e32 v122, v122, v138
	v_mul_f32_e32 v123, v123, v139
	v_mul_f32_e32 v124, v124, v140
	v_mul_f32_e32 v125, v125, v141
	v_mul_f32_e32 v126, v126, v142
	v_mul_f32_e32 v127, v127, v143
	v_mul_f32_e32 v144, v120, v120
	v_fmac_f32_e32 v144, v121, v121
	v_fmac_f32_e32 v144, v122, v122
	v_fmac_f32_e32 v144, v123, v123
	v_fmac_f32_e32 v144, v124, v124
	v_fmac_f32_e32 v144, v125, v125
	v_fmac_f32_e32 v144, v126, v126
	v_fmac_f32_e32 v144, v127, v127
	s_nop 1
	v_add_f32_dpp v144, v144, v144 quad_perm:[1,0,3,2] row_mask:0xf bank_mask:0xf
	s_nop 1
	v_add_f32_dpp v144, v144, v144 quad_perm:[2,3,0,1] row_mask:0xf bank_mask:0xf
	s_nop 1
	v_add_f32_dpp v144, v144, v144 row_half_mirror row_mask:0xf bank_mask:0xf
	v_fmamk_f32 v145, v144, 0x3c800000, v245
	v_rsq_f32_e32 v145, v145
	s_lshl_b32 s22, s10, 12
	s_add_u32 s22, s22, 0x10a00000
	v_mul_f32_e32 v120, v120, v145
	v_mul_f32_e32 v121, v121, v145
	v_mul_f32_e32 v122, v122, v145
	v_mul_f32_e32 v123, v123, v145
	v_mul_f32_e32 v124, v124, v145
	v_mul_f32_e32 v125, v125, v145
	v_mul_f32_e32 v126, v126, v145
	v_mul_f32_e32 v127, v127, v145
	v_cvt_pk_bf16_f32 v120, v120, v121
	v_cvt_pk_bf16_f32 v121, v122, v123
	v_cvt_pk_bf16_f32 v122, v124, v125
	v_cvt_pk_bf16_f32 v123, v126, v127
	buffer_store_dwordx4 v[120:123], v5, s[60:63], s22 offen sc1
	s_mul_i32 s17, s16, 3
	s_add_i32 s17, s10, s17
	s_cmp_lt_u32 s17, 0x4000
	s_cbranch_scc0 .Lcvm_pfskip_6
	s_and_b32 s21, s17, 0x7ff
	s_mul_i32 s19, s17, 0x2400
	s_add_u32 s19, s19, 0x3a00000
	s_sub_u32 s18, s19, 0x2400
	s_add_u32 s20, s19, 0x2400
	s_cmp_eq_u32 s21, 0
	s_cselect_b32 s18, s19, s18
	s_cmpk_eq_u32 s21, 0x7ff
	s_cselect_b32 s20, s19, s20
	buffer_load_dwordx4 v[60:63], v2, s[60:63], s18 offen
	buffer_load_dwordx4 v[64:67], v3, s[60:63], s18 offen
	buffer_load_dwordx4 v[68:71], v2, s[60:63], s19 offen
	buffer_load_dwordx4 v[72:75], v3, s[60:63], s19 offen
	buffer_load_dwordx4 v[76:79], v4, s[60:63], s19 offen
	buffer_load_dwordx4 v[80:83], v2, s[60:63], s20 offen
	buffer_load_dwordx4 v[84:87], v3, s[60:63], s20 offen
	s_branch .Lcvm_pfdone_6

; __device__ __forceinline__ void conv_mixer_rows(CArgs a, int layer, int G) {
;     ...
;     auto load = [&](int row, u32x4 (&raw)[7]) {
;         const int s = row & (SEQ - 1);
; #pragma unroll
;         for (int k = 0; k < 3; ++k) {
;             const int sp = s + k - 1; const int rr = (sp >= 0 && sp < SEQ) ? row + k - 1 : row;
;             const bf16_t* ur = U + (size_t)rr * NU;
;             u32x4 h = *(const u32x4*)(ur + UCH + c0), c = *(const u32x4*)(ur + UCC + c0);
;             if (!(sp >= 0 && sp < SEQ)) { h = (u32x4){0u, 0u, 0u, 0u}; c = (u32x4){0u, 0u, 0u, 0u}; }
;             raw[2 * k] = h; raw[2 * k + 1] = c;
;         }
;         raw[6] = *(const u32x4*)(U + (size_t)row * NU + UCB + c0);
;     };
.Lcvm_wg_7:
	s_and_b32 s21, s10, 0x7ff
	s_cmp_lg_u32 s21, 0
	s_cbranch_scc1 .Lcvm_nz0_3
	v_mov_b32_e32 v88, 0
	v_mov_b32_e32 v89, 0
	v_mov_b32_e32 v90, 0
	v_mov_b32_e32 v91, 0

; #define wt16(p, v) wt16b(WSB, (p), (v))
; __device__ __forceinline__ u32x4 pack8(const float (&f)[8]) { u32x4 v; v.x = cvt_pk_bf16(f[0], f[1]); v.y = cvt_pk_bf16(f[2], f[3]); v.z = cvt_pk_bf16(f[4], f[5]); v.w = cvt_pk_bf16(f[6], f[7]); return v; }
; __device__ __forceinline__ void conv_mixer_rows(CArgs a, int layer, int G) {
;     ...
;     auto finish = [&](int row, const u32x4 (&raw)[7]) {
;         float accv[8];
; #pragma unroll
;         for (int e = 0; e < 8; ++e) accv[e] = 0.f;
; #pragma unroll
;         for (int k = 0; k < 3; ++k) { float ch[8], cc[8]; unpack8(raw[2 * k], ch); unpack8(raw[2 * k + 1], cc);
; #pragma unroll
;             for (int e = 0; e < 8; ++e) accv[e] += w[k][e] * (cc[e] * ch[e]); }
;         float cbv[8]; unpack8(raw[6], cbv);
;         float ss = 0.f;
; #pragma unroll
;         for (int e = 0; e < 8; ++e) { accv[e] *= cbv[e]; ss += accv[e] * accv[e]; }
;         ss += __shfl_xor(ss, 1); ss += __shfl_xor(ss, 2); ss += __shfl_xor(ss, 4);
;         const float r = rsqrtf(ss * (1.f / 64.f) + EPS);
; #pragma unroll
;         for (int e = 0; e < 8; ++e) accv[e] *= r;
;         wt16(Y + (size_t)row * 2048 + 1536 + c0, pack8(accv));
;     };
;     for (int row = gw; row < T; row += 2 * NGW) {
;         const int row2 = row + NGW;
;         u32x4 ra[7], rb[7];
;         load(row, ra);
;         if (row2 < T) load(row2, rb);
;         finish(row, ra);
;         if (row2 < T) finish(row2, rb);
;     }
.Lcvm_nz2_3:
	v_lshlrev_b32_e32 v128, 16, v88
	v_and_b32_e32 v129, 0xffff0000, v88
	v_lshlrev_b32_e32 v130, 16, v89
	v_and_b32_e32 v131, 0xffff0000, v89
	v_lshlrev_b32_e32 v132, 16, v90
	v_and_b32_e32 v133, 0xffff0000, v90
	v_lshlrev_b32_e32 v134, 16, v91
	v_and_b32_e32 v135, 0xffff0000, v91
	v_lshlrev_b32_e32 v136, 16, v92
	v_and_b32_e32 v137, 0xffff0000, v92
	v_lshlrev_b32_e32 v138, 16, v93
	v_and_b32_e32 v139, 0xffff0000, v93
	v_lshlrev_b32_e32 v140, 16, v94
	v_and_b32_e32 v141, 0xffff0000, v94
	v_lshlrev_b32_e32 v142, 16, v95
	v_and_b32_e32 v143, 0xffff0000, v95
	v_mul_f32_e32 v128, v136, v128
	v_mul_f32_e32 v129, v137, v129
	v_mul_f32_e32 v130, v138, v130
	v_mul_f32_e32 v131, v139, v131
	v_mul_f32_e32 v132, v140, v132
	v_mul_f32_e32 v133, v141, v133
	v_mul_f32_e32 v134, v142, v134
	v_mul_f32_e32 v135, v143, v135
	v_mul_f32_e32 v120, v8, v128
	v_mul_f32_e32 v121, v9, v129
	v_mul_f32_e32 v122, v10, v130
	v_mul_f32_e32 v123, v11, v131
	v_mul_f32_e32 v124, v12, v132
	v_mul_f32_e32 v125, v13, v133
	v_mul_f32_e32 v126, v14, v134
	v_mul_f32_e32 v127, v15, v135
	v_lshlrev_b32_e32 v128, 16, v96
	v_and_b32_e32 v129, 0xffff0000, v96
	v_lshlrev_b32_e32 v130, 16, v97
	v_and_b32_e32 v131, 0xffff0000, v97
	v_lshlrev_b32_e32 v132, 16, v98
	v_and_b32_e32 v133, 0xffff0000, v98
	v_lshlrev_b32_e32 v134, 16, v99
	v_and_b32_e32 v135, 0xffff0000, v99
	v_lshlrev_b32_e32 v136, 16, v100
	v_and_b32_e32 v137, 0xffff0000, v100
	v_lshlrev_b32_e32 v138, 16, v101
	v_and_b32_e32 v139, 0xffff0000, v101
	v_lshlrev_b32_e32 v140, 16, v102
	v_and_b32_e32 v141, 0xffff0000, v102
	v_lshlrev_b32_e32 v142, 16, v103
	v_and_b32_e32 v143, 0xffff0000, v103
	v_mul_f32_e32 v128, v136, v128
	v_mul_f32_e32 v129, v137, v129
	v_mul_f32_e32 v130, v138, v130
	v_mul_f32_e32 v131, v139, v131
	v_mul_f32_e32 v132, v140, v132
	v_mul_f32_e32 v133, v141, v133
	v_mul_f32_e32 v134, v142, v134
	v_mul_f32_e32 v135, v143, v135
	v_fmac_f32_e32 v120, v16, v128
	v_fmac_f32_e32 v121, v17, v129
	v_fmac_f32_e32 v122, v18, v130
	v_fmac_f32_e32 v123, v19, v131
	v_fmac_f32_e32 v124, v20, v132
	v_fmac_f32_e32 v125, v21, v133
	v_fmac_f32_e32 v126, v22, v134
	v_fmac_f32_e32 v127, v23, v135
	v_lshlrev_b32_e32 v128, 16, v108
	v_and_b32_e32 v129, 0xffff0000, v108
	v_lshlrev_b32_e32 v130, 16, v109
	v_and_b32_e32 v131, 0xffff0000, v109
	v_lshlrev_b32_e32 v132, 16, v110
	v_and_b32_e32 v133, 0xffff0000, v110
	v_lshlrev_b32_e32 v134, 16, v111
	v_and_b32_e32 v135, 0xffff0000, v111
	v_lshlrev_b32_e32 v136, 16, v112
	v_and_b32_e32 v137, 0xffff0000, v112
	v_lshlrev_b32_e32 v138, 16, v113
	v_and_b32_e32 v139, 0xffff0000, v113
	v_lshlrev_b32_e32 v140, 16, v114
	v_and_b32_e32 v141, 0xffff0000, v114
	v_lshlrev_b32_e32 v142, 16, v115
	v_and_b32_e32 v143, 0xffff0000, v115
	v_mul_f32_e32 v128, v136, v128
	v_mul_f32_e32 v129, v137, v129
	v_mul_f32_e32 v130, v138, v130
	v_mul_f32_e32 v131, v139, v131
	v_mul_f32_e32 v132, v140, v132
	v_mul_f32_e32 v133, v141, v133
	v_mul_f32_e32 v134, v142, v134
	v_mul_f32_e32 v135, v143, v135
	v_fmac_f32_e32 v120, v24, v128
	v_fmac_f32_e32 v121, v25, v129
	v_fmac_f32_e32 v122, v26, v130
	v_fmac_f32_e32 v123, v27, v131
	v_fmac_f32_e32 v124, v28, v132
	v_fmac_f32_e32 v125, v29, v133
	v_fmac_f32_e32 v126, v30, v134
	v_fmac_f32_e32 v127, v31, v135
	v_lshlrev_b32_e32 v136, 16, v104
	v_and_b32_e32 v137, 0xffff0000, v104
	v_lshlrev_b32_e32 v138, 16, v105
	v_and_b32_e32 v139, 0xffff0000, v105
	v_lshlrev_b32_e32 v140, 16, v106
	v_and_b32_e32 v141, 0xffff0000, v106
	v_lshlrev_b32_e32 v142, 16, v107
	v_and_b32_e32 v143, 0xffff0000, v107
	v_mul_f32_e32 v120, v120, v136
	v_mul_f32_e32 v121, v121, v137
	v_mul_f32_e32 v122, v122, v138
	v_mul_f32_e32 v123, v123, v139
	v_mul_f32_e32 v124, v124, v140
	v_mul_f32_e32 v125, v125, v141
	v_mul_f32_e32 v126, v126, v142
	v_mul_f32_e32 v127, v127, v143
	v_mul_f32_e32 v144, v120, v120
	v_fmac_f32_e32 v144, v121, v121
	v_fmac_f32_e32 v144, v122, v122
	v_fmac_f32_e32 v144, v123, v123
	v_fmac_f32_e32 v144, v124, v124
	v_fmac_f32_e32 v144, v125, v125
	v_fmac_f32_e32 v144, v126, v126
	v_fmac_f32_e32 v144, v127, v127
	s_nop 1
	v_add_f32_dpp v144, v144, v144 quad_perm:[1,0,3,2] row_mask:0xf bank_mask:0xf
	s_nop 1
	v_add_f32_dpp v144, v144, v144 quad_perm:[2,3,0,1] row_mask:0xf bank_mask:0xf
	s_nop 1
	v_add_f32_dpp v144, v144, v144 row_half_mirror row_mask:0xf bank_mask:0xf
	v_fmamk_f32 v145, v144, 0x3c800000, v245
	v_rsq_f32_e32 v145, v145
	s_lshl_b32 s22, s10, 12
	s_add_u32 s22, s22, 0x10a00000
	v_mul_f32_e32 v120, v120, v145
	v_mul_f32_e32 v121, v121, v145
	v_mul_f32_e32 v122, v122, v145
	v_mul_f32_e32 v123, v123, v145
	v_mul_f32_e32 v124, v124, v145
	v_mul_f32_e32 v125, v125, v145
	v_mul_f32_e32 v126, v126, v145
	v_mul_f32_e32 v127, v127, v145
	v_cvt_pk_bf16_f32 v120, v120, v121
	v_cvt_pk_bf16_f32 v121, v122, v123
	v_cvt_pk_bf16_f32 v122, v124, v125
	v_cvt_pk_bf16_f32 v123, v126, v127
	buffer_store_dwordx4 v[120:123], v5, s[60:63], s22 offen sc1
	s_mul_i32 s17, s16, 3
	s_add_i32 s17, s10, s17
	s_cmp_lt_u32 s17, 0x4000
	s_cbranch_scc0 .Lcvm_pfskip_8
	s_and_b32 s21, s17, 0x7ff
	s_mul_i32 s19, s17, 0x2400
	s_add_u32 s19, s19, 0x3a00000
	s_sub_u32 s18, s19, 0x2400
	s_add_u32 s20, s19, 0x2400
	s_cmp_eq_u32 s21, 0
	s_cselect_b32 s18, s19, s18
	s_cmpk_eq_u32 s21, 0x7ff
	s_cselect_b32 s20, s19, s20
	buffer_load_dwordx4 v[88:91], v2, s[60:63], s18 offen
	buffer_load_dwordx4 v[92:95], v3, s[60:63], s18 offen
	buffer_load_dwordx4 v[96:99], v2, s[60:63], s19 offen
	buffer_load_dwordx4 v[100:103], v3, s[60:63], s19 offen
	buffer_load_dwordx4 v[104:107], v4, s[60:63], s19 offen
	buffer_load_dwordx4 v[108:111], v2, s[60:63], s20 offen
	buffer_load_dwordx4 v[112:115], v3, s[60:63], s20 offen
	s_branch .Lcvm_pfdone_8

; __device__ __forceinline__ void conv_mixer_rows(CArgs a, int layer, int G) {
;     ...
;     for (int row = gw; row < T; row += 2 * NGW) {
;         const int row2 = row + NGW;
;         u32x4 ra[7], rb[7];
;         load(row, ra);
;         if (row2 < T) load(row2, rb);
;         finish(row, ra);
;         if (row2 < T) finish(row2, rb);
;     }
.Lcvm_pfdone_8:
	s_add_i32 s10, s10, s16
	s_cmp_lt_u32 s10, 0x4000
	s_cbranch_scc0 .Lcvm_done

; __device__ __forceinline__ void conv_mixer_rows(CArgs a, int layer, int G) {
;     ...
;     for (int row = gw; row < T; row += 2 * NGW) {
;         const int row2 = row + NGW;
;         u32x4 ra[7], rb[7];
;         load(row, ra);
;         if (row2 < T) load(row2, rb);
;         finish(row, ra);
;         if (row2 < T) finish(row2, rb);
;     }
.Lcvm_pfdone_14:
	s_add_i32 s10, s10, s16
	s_cmp_lt_u32 s10, 0x4000
	s_cbranch_scc0 .Lcvm_done
	s_branch .Lcvm_loop
